# v34 + the two As[1][1] LDS-DMA loads of P1/P7 also in saddr form (8 of 16 address adds per pass removed there)
# baseline (speedup 1.0000x reference)
; #define PG8_STAGE(bufoff, gbase, voff) do { _Pragma("unroll") for (int _i = 0; _i < 2; ++_i) \
;         __builtin_amdgcn_global_load_lds((const unsigned*)((const char*)(gbase) + (voff)[_i]), (PG8_LAS unsigned*)(lds + (bufoff) + ldsw + _i * 8192), 16, 0, 0); } while (0)
; #define PG8_LDA(dst, b, h) do { _Pragma("unroll") for (int m = 0; m < 4; ++m) _Pragma("unroll") for (int k = 0; k < 2; ++k) dst[m][k] = *(const PG8_LAS bf16x8*)(lds + PG8_SA(b, h) + aoff + m * 2048 + k * 1024); } while (0)
; #define PG8_LDB(dst, b, h) do { _Pragma("unroll") for (int n = 0; n < 2; ++n) _Pragma("unroll") for (int k = 0; k < 2; ++k) dst[n][k] = *(const PG8_LAS bf16x8*)(lds + PG8_SB(b, h) + boff + n * 2048 + k * 1024); } while (0)
; #define PG8_WAIT_V(n) asm volatile("s_waitcnt vmcnt(" #n ")" ::: "memory")
; #define PG8_WAIT_L(n) asm volatile("s_waitcnt lgkmcnt(" #n ")" ::: "memory")
; #define PG8_BAR __builtin_amdgcn_s_barrier()
; #define PG8_SCHED __builtin_amdgcn_sched_barrier(0)
; template <class Epi, class Sched, bool ALIGN_EPI = false, bool SP2 = false>
; __device__ __forceinline__ void gemm_phase(PG8_LAS unsigned char* lds, const Gemm g, const Sched& S, const Epi& E) {
;     ...
;         const bool has_next = S.next(ui + 1, nxt);
;         const char* nA = has_next ? (const char*)g.A + (size_t)nxt.pm * tstep : cA; const char* nB = has_next ? (const char*)g.Bt + (size_t)nxt.pn * tstep : cB;
;         for (int t = 0; t < nt; t += 2) {
;             if constexpr (Epi::HAS_MID) { if (t == nt / 2) E.mid(acc, cur, wr, wc, fr, fq); }
;             const bool last = (t == nt - 2);
;             const char* a1 = cA + (size_t)(t + 1) * kstep;
;             const char* a2 = last ? nA : cA + (size_t)(t + 2) * kstep; const char* b2 = last ? nB : cB + (size_t)(t + 2) * kstep;
;             const char* a3 = a2 + kstep; const char* b3 = b2 + kstep;
;             if (last && has_next) S.a_ready(nxt);
;             if constexpr (SP2) {
;             PG8_LDB(B0, 0, 0); PG8_LDB(B1, 0, 1); PG8_SCHED; PG8_LDA(At, 0, 0); PG8_STAGE(PG8_SA(1, 1), a1 + hstep, voffA);
;             PG8_WAIT_V(8); PG8_WAIT_L(0); PG8_BAR; PG8_MMA(0, 0, At, B0); PG8_MMA(0, 1, At, B1); PG8_BAR; PG8_SCHED;
;             PG8_LDA(At, 0, 1); PG8_STAGE(PG8_SB(0, 0), b2, voffB); PG8_STAGE(PG8_SB(0, 1), b2 + hstepB, voffB); PG8_STAGE(PG8_SA(0, 0), a2, voffA);
.LBB0_191:
	s_ashr_i32 s13, s12, 31
	s_lshl_b64 s[14:15], s[12:13], 19
	v_readlane_b32 s16, v241, 53
	v_readlane_b32 s17, v241, 54
	s_add_u32 s14, s16, s14
	s_addc_u32 s15, s17, s15
	s_and_b64 s[16:17], s[2:3], exec
	s_cselect_b32 s5, s15, s21
	s_cselect_b32 s13, s14, s20
	s_ashr_i32 s11, s10, 31
	s_lshl_b64 s[16:17], s[10:11], 19
	v_readlane_b32 s24, v241, 36
	v_readlane_b32 s25, v241, 37
	s_add_u32 s16, s24, s16
	s_addc_u32 s17, s25, s17
	s_and_b64 s[24:25], s[2:3], exec
	s_cselect_b32 s11, s17, s23
	s_cselect_b32 s19, s16, s22
	s_add_u32 s20, s20, 0x40080
	s_addc_u32 s21, s21, 0
	s_add_u32 s73, s22, 0x100
	s_addc_u32 s74, s23, 0
	s_mov_b32 s75, -2
	ds_read_b128 v[146:149], v152
	ds_read_b128 v[156:159], v152 offset:1024
	ds_read_b128 v[160:163], v152 offset:2048
	ds_read_b128 v[164:167], v152 offset:3072
	ds_read_b128 v[168:171], v153
	ds_read_b128 v[172:175], v153 offset:1024
	ds_read_b128 v[176:179], v153 offset:2048
	ds_read_b128 v[180:183], v153 offset:3072
	s_add_u32 s22, s20, 0xfffc0080
	s_addc_u32 s23, s21, -1
	s_cmp_eq_u32 s75, 12
	s_cselect_b32 s25, s5, s23
	s_cselect_b32 s24, s13, s22
	s_cselect_b32 s23, s11, s74
	s_cselect_b32 s22, s19, s73
	s_add_i32 m0, s27, 0xc000
	ds_read_b128 v[184:187], v154
	ds_read_b128 v[188:191], v154 offset:1024
	ds_read_b128 v[192:195], v154 offset:2048
	ds_read_b128 v[196:199], v154 offset:3072
	ds_read_b128 v[200:203], v154 offset:4096
	ds_read_b128 v[204:207], v154 offset:5120
	ds_read_b128 v[208:211], v154 offset:6144
	ds_read_b128 v[212:215], v154 offset:7168
	global_load_lds_dwordx4 v138, s[20:21]
	s_add_i32 m0, s27, 0xe000
	s_nop 0
	global_load_lds_dwordx4 v140, s[20:21]
	s_waitcnt vmcnt(8)
	s_waitcnt lgkmcnt(0)
	s_barrier
	v_mfma_f32_16x16x32_bf16 v[126:129], v[146:149], v[184:187], 0
	v_mfma_f32_16x16x32_bf16 v[122:125], v[160:163], v[184:187], 0
	v_mfma_f32_16x16x32_bf16 v[114:117], v[146:149], v[192:195], 0
	v_mfma_f32_16x16x32_bf16 v[106:109], v[160:163], v[192:195], 0
	v_mfma_f32_16x16x32_bf16 v[98:101], v[146:149], v[200:203], 0
	v_mfma_f32_16x16x32_bf16 v[90:93], v[160:163], v[200:203], 0
	v_mfma_f32_16x16x32_bf16 v[82:85], v[146:149], v[208:211], 0
	v_mfma_f32_16x16x32_bf16 v[74:77], v[160:163], v[208:211], 0
	v_mfma_f32_16x16x32_bf16 v[126:129], v[156:159], v[188:191], v[126:129]
	v_mfma_f32_16x16x32_bf16 v[122:125], v[164:167], v[188:191], v[122:125]
	v_mfma_f32_16x16x32_bf16 v[114:117], v[156:159], v[196:199], v[114:117]
	v_mfma_f32_16x16x32_bf16 v[106:109], v[164:167], v[196:199], v[106:109]
	v_mfma_f32_16x16x32_bf16 v[98:101], v[156:159], v[204:207], v[98:101]
	v_mfma_f32_16x16x32_bf16 v[90:93], v[164:167], v[204:207], v[90:93]
	v_mfma_f32_16x16x32_bf16 v[82:85], v[156:159], v[212:215], v[82:85]
	v_mfma_f32_16x16x32_bf16 v[74:77], v[164:167], v[212:215], v[74:77]
	v_mfma_f32_16x16x32_bf16 v[118:121], v[168:171], v[184:187], 0
	v_mfma_f32_16x16x32_bf16 v[110:113], v[176:179], v[184:187], 0
	v_mfma_f32_16x16x32_bf16 v[102:105], v[168:171], v[192:195], 0
	v_mfma_f32_16x16x32_bf16 v[94:97], v[176:179], v[192:195], 0
	v_mfma_f32_16x16x32_bf16 v[86:89], v[168:171], v[200:203], 0
	v_mfma_f32_16x16x32_bf16 v[78:81], v[176:179], v[200:203], 0
	v_mfma_f32_16x16x32_bf16 v[70:73], v[168:171], v[208:211], 0
	v_mfma_f32_16x16x32_bf16 v[66:69], v[176:179], v[208:211], 0
	v_mfma_f32_16x16x32_bf16 v[118:121], v[172:175], v[188:191], v[118:121]
	v_mfma_f32_16x16x32_bf16 v[110:113], v[180:183], v[188:191], v[110:113]
	v_mfma_f32_16x16x32_bf16 v[102:105], v[172:175], v[196:199], v[102:105]
	v_mfma_f32_16x16x32_bf16 v[94:97], v[180:183], v[196:199], v[94:97]
	v_mfma_f32_16x16x32_bf16 v[86:89], v[172:175], v[204:207], v[86:89]
	v_mfma_f32_16x16x32_bf16 v[78:81], v[180:183], v[204:207], v[78:81]
	v_mfma_f32_16x16x32_bf16 v[70:73], v[172:175], v[212:215], v[70:73]
	v_mfma_f32_16x16x32_bf16 v[66:69], v[180:183], v[212:215], v[66:69]
	s_barrier
	s_add_i32 s76, s69, s26
	v_lshl_add_u64 v[216:217], s[22:23], 0, v[132:133]
	s_mov_b32 m0, s76
	ds_read_b128 v[184:187], v154 offset:16384
	ds_read_b128 v[188:191], v154 offset:17408
	ds_read_b128 v[192:195], v154 offset:18432
	ds_read_b128 v[196:199], v154 offset:19456
	ds_read_b128 v[200:203], v154 offset:20480
	ds_read_b128 v[204:207], v154 offset:21504
	ds_read_b128 v[208:211], v154 offset:22528
	ds_read_b128 v[212:215], v154 offset:23552
	global_load_lds_dwordx4 v132, s[22:23]
	s_add_i32 m0, s76, 0x2000
	s_add_u32 s76, s22, 0x10000
	v_lshl_add_u64 v[218:219], s[22:23], 0, v[136:137]
	s_addc_u32 s77, s23, 0
	s_add_i32 s78, s70, s26
	global_load_lds_dwordx4 v136, s[22:23]
	s_mov_b32 m0, s78
	v_lshl_add_u64 v[222:223], s[24:25], 0, v[134:135]
	global_load_lds_dwordx4 v132, s[76:77]
	s_add_i32 m0, s78, 0x2000
	s_nop 0
	global_load_lds_dwordx4 v136, s[76:77]
	v_lshl_add_u64 v[220:221], s[24:25], 0, v[130:131]
	s_mov_b32 m0, s27
	s_nop 0
	global_load_lds_dwordx4 v130, s[24:25]
	s_mov_b32 m0, s28
	s_nop 0
	global_load_lds_dwordx4 v134, s[24:25]
	s_waitcnt vmcnt(8)
	s_waitcnt lgkmcnt(0)
	s_barrier
; #define PG8_STAGE(bufoff, gbase, voff) do { _Pragma("unroll") for (int _i = 0; _i < 2; ++_i) \
;         __builtin_amdgcn_global_load_lds((const unsigned*)((const char*)(gbase) + (voff)[_i]), (PG8_LAS unsigned*)(lds + (bufoff) + ldsw + _i * 8192), 16, 0, 0); } while (0)
; #define PG8_LDA(dst, b, h) do { _Pragma("unroll") for (int m = 0; m < 4; ++m) _Pragma("unroll") for (int k = 0; k < 2; ++k) dst[m][k] = *(const PG8_LAS bf16x8*)(lds + PG8_SA(b, h) + aoff + m * 2048 + k * 1024); } while (0)
; #define PG8_LDB(dst, b, h) do { _Pragma("unroll") for (int n = 0; n < 2; ++n) _Pragma("unroll") for (int k = 0; k < 2; ++k) dst[n][k] = *(const PG8_LAS bf16x8*)(lds + PG8_SB(b, h) + boff + n * 2048 + k * 1024); } while (0)
; #define PG8_MMA(ai, bj, At, Bt) do { __builtin_amdgcn_s_setprio(1); _Pragma("unroll") for (int m = 0; m < 4; ++m) _Pragma("unroll") for (int n = 0; n < 2; ++n) _Pragma("unroll") for (int k = 0; k < 2; ++k) \
;         acc[ai][bj][m][n] = __builtin_amdgcn_mfma_f32_16x16x32_bf16(Bt[n][k], At[m][k], acc[ai][bj][m][n], 0, 0, 0); __builtin_amdgcn_s_setprio(0); } while (0)
; #define PG8_WAIT_V(n) asm volatile("s_waitcnt vmcnt(" #n ")" ::: "memory")
; #define PG8_WAIT_L(n) asm volatile("s_waitcnt lgkmcnt(" #n ")" ::: "memory")
; #define PG8_BAR __builtin_amdgcn_s_barrier()
; #define PG8_SCHED __builtin_amdgcn_sched_barrier(0)
; template <class Epi, class Sched, bool ALIGN_EPI = false, bool SP2 = false>
; __device__ __forceinline__ void gemm_phase(PG8_LAS unsigned char* lds, const Gemm g, const Sched& S, const Epi& E) {
;     ...
;             PG8_WAIT_V(8); PG8_WAIT_L(0); PG8_BAR; PG8_MMA(1, 0, At, B0); PG8_MMA(1, 1, At, B1); PG8_BAR; PG8_SCHED;
;             PG8_LDB(B0, 1, 0); PG8_LDB(B1, 1, 1); PG8_SCHED; PG8_LDA(At, 1, 0); PG8_STAGE(PG8_SA(0, 1), a2 + hstep, voffA);
;             PG8_WAIT_V(8); PG8_WAIT_L(0); PG8_BAR; PG8_MMA(0, 0, At, B0); PG8_MMA(0, 1, At, B1); PG8_BAR; PG8_SCHED;
	v_mfma_f32_16x16x32_bf16 v[62:65], v[146:149], v[184:187], 0
	v_mfma_f32_16x16x32_bf16 v[58:61], v[160:163], v[184:187], 0
	v_mfma_f32_16x16x32_bf16 v[50:53], v[146:149], v[192:195], 0
	v_mfma_f32_16x16x32_bf16 v[42:45], v[160:163], v[192:195], 0
	v_mfma_f32_16x16x32_bf16 v[34:37], v[146:149], v[200:203], 0
	v_mfma_f32_16x16x32_bf16 v[26:29], v[160:163], v[200:203], 0
	v_mfma_f32_16x16x32_bf16 v[18:21], v[146:149], v[208:211], 0
	v_mfma_f32_16x16x32_bf16 v[10:13], v[160:163], v[208:211], 0
	v_mfma_f32_16x16x32_bf16 v[62:65], v[156:159], v[188:191], v[62:65]
	v_mfma_f32_16x16x32_bf16 v[58:61], v[164:167], v[188:191], v[58:61]
	v_mfma_f32_16x16x32_bf16 v[50:53], v[156:159], v[196:199], v[50:53]
	v_mfma_f32_16x16x32_bf16 v[42:45], v[164:167], v[196:199], v[42:45]
	v_mfma_f32_16x16x32_bf16 v[34:37], v[156:159], v[204:207], v[34:37]
	v_mfma_f32_16x16x32_bf16 v[26:29], v[164:167], v[204:207], v[26:29]
	v_mfma_f32_16x16x32_bf16 v[18:21], v[156:159], v[212:215], v[18:21]
	v_mfma_f32_16x16x32_bf16 v[10:13], v[164:167], v[212:215], v[10:13]
	v_mfma_f32_16x16x32_bf16 v[54:57], v[168:171], v[184:187], 0
	v_mfma_f32_16x16x32_bf16 v[46:49], v[176:179], v[184:187], 0
	v_mfma_f32_16x16x32_bf16 v[38:41], v[168:171], v[192:195], 0
	v_mfma_f32_16x16x32_bf16 v[30:33], v[176:179], v[192:195], 0
	v_mfma_f32_16x16x32_bf16 v[22:25], v[168:171], v[200:203], 0
	v_mfma_f32_16x16x32_bf16 v[14:17], v[176:179], v[200:203], 0
	v_mfma_f32_16x16x32_bf16 v[6:9], v[168:171], v[208:211], 0
	v_mfma_f32_16x16x32_bf16 v[2:5], v[176:179], v[208:211], 0
	v_mfma_f32_16x16x32_bf16 v[54:57], v[172:175], v[188:191], v[54:57]
	v_mfma_f32_16x16x32_bf16 v[46:49], v[180:183], v[188:191], v[46:49]
	v_mfma_f32_16x16x32_bf16 v[38:41], v[172:175], v[196:199], v[38:41]
	v_mfma_f32_16x16x32_bf16 v[30:33], v[180:183], v[196:199], v[30:33]
	v_mfma_f32_16x16x32_bf16 v[22:25], v[172:175], v[204:207], v[22:25]
	v_mfma_f32_16x16x32_bf16 v[14:17], v[180:183], v[204:207], v[14:17]
	v_mfma_f32_16x16x32_bf16 v[6:9], v[172:175], v[212:215], v[6:9]
	v_mfma_f32_16x16x32_bf16 v[2:5], v[180:183], v[212:215], v[2:5]
	s_barrier
	s_add_i32 s76, 0, 0x18000
	v_add_u32_e32 v155, s76, v150
	s_add_i32 s77, 0, 0x1c000
	ds_read_b128 v[146:149], v155
	ds_read_b128 v[156:159], v155 offset:1024
	ds_read_b128 v[160:163], v155 offset:2048
	ds_read_b128 v[164:167], v155 offset:3072
	v_add_u32_e32 v155, s77, v150
	ds_read_b128 v[168:171], v155
	ds_read_b128 v[172:175], v155 offset:1024
	ds_read_b128 v[176:179], v155 offset:2048
	ds_read_b128 v[180:183], v155 offset:3072
	s_add_u32 s24, s24, 0x40000
	s_addc_u32 s25, s25, 0
	s_mov_b32 m0, s29
	ds_read_b128 v[184:187], v154 offset:32768
	ds_read_b128 v[188:191], v154 offset:33792
	ds_read_b128 v[192:195], v154 offset:34816
	ds_read_b128 v[196:199], v154 offset:35840
	ds_read_b128 v[200:203], v154 offset:36864
	ds_read_b128 v[204:207], v154 offset:37888
	ds_read_b128 v[208:211], v154 offset:38912
	ds_read_b128 v[212:215], v154 offset:39936
	global_load_lds_dwordx4 v130, s[24:25]
	s_mov_b32 m0, s30
	s_nop 0
	global_load_lds_dwordx4 v134, s[24:25]
	s_waitcnt vmcnt(8)
	s_waitcnt lgkmcnt(0)
	s_barrier
	v_mfma_f32_16x16x32_bf16 v[126:129], v[146:149], v[184:187], v[126:129]
	v_mfma_f32_16x16x32_bf16 v[122:125], v[160:163], v[184:187], v[122:125]
	v_mfma_f32_16x16x32_bf16 v[114:117], v[146:149], v[192:195], v[114:117]
	v_mfma_f32_16x16x32_bf16 v[106:109], v[160:163], v[192:195], v[106:109]
	v_mfma_f32_16x16x32_bf16 v[98:101], v[146:149], v[200:203], v[98:101]
	v_mfma_f32_16x16x32_bf16 v[90:93], v[160:163], v[200:203], v[90:93]
	v_mfma_f32_16x16x32_bf16 v[82:85], v[146:149], v[208:211], v[82:85]
	v_mfma_f32_16x16x32_bf16 v[74:77], v[160:163], v[208:211], v[74:77]
	v_mfma_f32_16x16x32_bf16 v[126:129], v[156:159], v[188:191], v[126:129]
	v_mfma_f32_16x16x32_bf16 v[122:125], v[164:167], v[188:191], v[122:125]
	v_mfma_f32_16x16x32_bf16 v[114:117], v[156:159], v[196:199], v[114:117]
	v_mfma_f32_16x16x32_bf16 v[106:109], v[164:167], v[196:199], v[106:109]
	v_mfma_f32_16x16x32_bf16 v[98:101], v[156:159], v[204:207], v[98:101]
	v_mfma_f32_16x16x32_bf16 v[90:93], v[164:167], v[204:207], v[90:93]
	v_mfma_f32_16x16x32_bf16 v[82:85], v[156:159], v[212:215], v[82:85]
	v_mfma_f32_16x16x32_bf16 v[74:77], v[164:167], v[212:215], v[74:77]
	v_mfma_f32_16x16x32_bf16 v[118:121], v[168:171], v[184:187], v[118:121]
	v_mfma_f32_16x16x32_bf16 v[110:113], v[176:179], v[184:187], v[110:113]
	v_mfma_f32_16x16x32_bf16 v[102:105], v[168:171], v[192:195], v[102:105]
	v_mfma_f32_16x16x32_bf16 v[94:97], v[176:179], v[192:195], v[94:97]
	v_mfma_f32_16x16x32_bf16 v[86:89], v[168:171], v[200:203], v[86:89]
	v_mfma_f32_16x16x32_bf16 v[78:81], v[176:179], v[200:203], v[78:81]
	v_mfma_f32_16x16x32_bf16 v[70:73], v[168:171], v[208:211], v[70:73]
	v_mfma_f32_16x16x32_bf16 v[66:69], v[176:179], v[208:211], v[66:69]
	v_mfma_f32_16x16x32_bf16 v[118:121], v[172:175], v[188:191], v[118:121]
	v_mfma_f32_16x16x32_bf16 v[110:113], v[180:183], v[188:191], v[110:113]
	v_mfma_f32_16x16x32_bf16 v[102:105], v[172:175], v[196:199], v[102:105]
	v_mfma_f32_16x16x32_bf16 v[94:97], v[180:183], v[196:199], v[94:97]
	v_mfma_f32_16x16x32_bf16 v[86:89], v[172:175], v[204:207], v[86:89]
	v_mfma_f32_16x16x32_bf16 v[78:81], v[180:183], v[204:207], v[78:81]
	v_mfma_f32_16x16x32_bf16 v[70:73], v[172:175], v[212:215], v[70:73]
	v_mfma_f32_16x16x32_bf16 v[66:69], v[180:183], v[212:215], v[66:69]
	s_barrier
; #define PG8_STAGE(bufoff, gbase, voff) do { _Pragma("unroll") for (int _i = 0; _i < 2; ++_i) \
;         __builtin_amdgcn_global_load_lds((const unsigned*)((const char*)(gbase) + (voff)[_i]), (PG8_LAS unsigned*)(lds + (bufoff) + ldsw + _i * 8192), 16, 0, 0); } while (0)
; #define PG8_LDA(dst, b, h) do { _Pragma("unroll") for (int m = 0; m < 4; ++m) _Pragma("unroll") for (int k = 0; k < 2; ++k) dst[m][k] = *(const PG8_LAS bf16x8*)(lds + PG8_SA(b, h) + aoff + m * 2048 + k * 1024); } while (0)
; #define PG8_LDB(dst, b, h) do { _Pragma("unroll") for (int n = 0; n < 2; ++n) _Pragma("unroll") for (int k = 0; k < 2; ++k) dst[n][k] = *(const PG8_LAS bf16x8*)(lds + PG8_SB(b, h) + boff + n * 2048 + k * 1024); } while (0)
; #define PG8_MMA(ai, bj, At, Bt) do { __builtin_amdgcn_s_setprio(1); _Pragma("unroll") for (int m = 0; m < 4; ++m) _Pragma("unroll") for (int n = 0; n < 2; ++n) _Pragma("unroll") for (int k = 0; k < 2; ++k) \
;         acc[ai][bj][m][n] = __builtin_amdgcn_mfma_f32_16x16x32_bf16(Bt[n][k], At[m][k], acc[ai][bj][m][n], 0, 0, 0); __builtin_amdgcn_s_setprio(0); } while (0)
; #define PG8_WAIT_V(n) asm volatile("s_waitcnt vmcnt(" #n ")" ::: "memory")
; #define PG8_WAIT_L(n) asm volatile("s_waitcnt lgkmcnt(" #n ")" ::: "memory")
; #define PG8_BAR __builtin_amdgcn_s_barrier()
; #define PG8_SCHED __builtin_amdgcn_sched_barrier(0)
; template <class Epi, class Sched, bool ALIGN_EPI = false, bool SP2 = false>
; __device__ __forceinline__ void gemm_phase(PG8_LAS unsigned char* lds, const Gemm g, const Sched& S, const Epi& E) {
;     ...
;             if constexpr (SP2) {
;             PG8_LDB(B0, 0, 0); PG8_LDB(B1, 0, 1); PG8_SCHED; PG8_LDA(At, 0, 0); PG8_STAGE(PG8_SA(1, 1), a1 + hstep, voffA);
;             PG8_WAIT_V(8); PG8_WAIT_L(0); PG8_BAR; PG8_MMA(0, 0, At, B0); PG8_MMA(0, 1, At, B1); PG8_BAR; PG8_SCHED;
;     ...
;             PG8_LDA(At, 1, 1); PG8_STAGE(PG8_SB(1, 0), b3, voffB); PG8_STAGE(PG8_SB(1, 1), b3 + hstepB, voffB); PG8_STAGE(PG8_SA(1, 0), a3, voffA);
;             PG8_WAIT_V(8); PG8_WAIT_L(0); PG8_BAR; PG8_MMA(1, 0, At, B0); PG8_MMA(1, 1, At, B1); PG8_BAR; PG8_SCHED;
	s_add_i32 s24, s76, s26
	v_lshl_add_u64 v[216:217], v[216:217], 0, s[6:7]
	s_mov_b32 m0, s24
	ds_read_b128 v[184:187], v154 offset:49152
	ds_read_b128 v[188:191], v154 offset:50176
	ds_read_b128 v[192:195], v154 offset:51200
	ds_read_b128 v[196:199], v154 offset:52224
	ds_read_b128 v[200:203], v154 offset:53248
	ds_read_b128 v[204:207], v154 offset:54272
	ds_read_b128 v[208:211], v154 offset:55296
	ds_read_b128 v[212:215], v154 offset:56320
	global_load_lds_dwordx4 v[216:217], off
	s_add_i32 m0, s24, 0x2000
	s_add_u32 s22, s22, 0x10080
	v_lshl_add_u64 v[216:217], v[218:219], 0, s[6:7]
	s_addc_u32 s23, s23, 0
	s_add_i32 s24, s77, s26
	global_load_lds_dwordx4 v[216:217], off
	s_mov_b32 m0, s24
	s_nop 0
	global_load_lds_dwordx4 v132, s[22:23]
	s_add_i32 m0, s24, 0x2000
	s_nop 0
	global_load_lds_dwordx4 v136, s[22:23]
	v_lshl_add_u64 v[216:217], v[220:221], 0, s[6:7]
	s_mov_b32 m0, s33
	s_nop 0
	global_load_lds_dwordx4 v[216:217], off
	v_lshl_add_u64 v[216:217], v[222:223], 0, s[6:7]
	s_mov_b32 m0, s34
	s_nop 0
	global_load_lds_dwordx4 v[216:217], off
	s_waitcnt vmcnt(8)
	s_waitcnt lgkmcnt(0)
	s_barrier
	v_mfma_f32_16x16x32_bf16 v[62:65], v[146:149], v[184:187], v[62:65]
	v_mfma_f32_16x16x32_bf16 v[58:61], v[160:163], v[184:187], v[58:61]
	v_mfma_f32_16x16x32_bf16 v[50:53], v[146:149], v[192:195], v[50:53]
	v_mfma_f32_16x16x32_bf16 v[42:45], v[160:163], v[192:195], v[42:45]
	v_mfma_f32_16x16x32_bf16 v[34:37], v[146:149], v[200:203], v[34:37]
	v_mfma_f32_16x16x32_bf16 v[26:29], v[160:163], v[200:203], v[26:29]
	v_mfma_f32_16x16x32_bf16 v[18:21], v[146:149], v[208:211], v[18:21]
	v_mfma_f32_16x16x32_bf16 v[10:13], v[160:163], v[208:211], v[10:13]
	v_mfma_f32_16x16x32_bf16 v[62:65], v[156:159], v[188:191], v[62:65]
	v_mfma_f32_16x16x32_bf16 v[58:61], v[164:167], v[188:191], v[58:61]
	v_mfma_f32_16x16x32_bf16 v[50:53], v[156:159], v[196:199], v[50:53]
	v_mfma_f32_16x16x32_bf16 v[42:45], v[164:167], v[196:199], v[42:45]
	v_mfma_f32_16x16x32_bf16 v[34:37], v[156:159], v[204:207], v[34:37]
	v_mfma_f32_16x16x32_bf16 v[26:29], v[164:167], v[204:207], v[26:29]
	v_mfma_f32_16x16x32_bf16 v[18:21], v[156:159], v[212:215], v[18:21]
	v_mfma_f32_16x16x32_bf16 v[10:13], v[164:167], v[212:215], v[10:13]
	v_mfma_f32_16x16x32_bf16 v[54:57], v[168:171], v[184:187], v[54:57]
	v_mfma_f32_16x16x32_bf16 v[46:49], v[176:179], v[184:187], v[46:49]
	v_mfma_f32_16x16x32_bf16 v[38:41], v[168:171], v[192:195], v[38:41]
	v_mfma_f32_16x16x32_bf16 v[30:33], v[176:179], v[192:195], v[30:33]
	v_mfma_f32_16x16x32_bf16 v[22:25], v[168:171], v[200:203], v[22:25]
	v_mfma_f32_16x16x32_bf16 v[14:17], v[176:179], v[200:203], v[14:17]
	v_mfma_f32_16x16x32_bf16 v[6:9], v[168:171], v[208:211], v[6:9]
	v_mfma_f32_16x16x32_bf16 v[2:5], v[176:179], v[208:211], v[2:5]
	v_mfma_f32_16x16x32_bf16 v[54:57], v[172:175], v[188:191], v[54:57]
	v_mfma_f32_16x16x32_bf16 v[46:49], v[180:183], v[188:191], v[46:49]
	v_mfma_f32_16x16x32_bf16 v[38:41], v[172:175], v[196:199], v[38:41]
	v_mfma_f32_16x16x32_bf16 v[30:33], v[180:183], v[196:199], v[30:33]
	v_mfma_f32_16x16x32_bf16 v[22:25], v[172:175], v[204:207], v[22:25]
	v_mfma_f32_16x16x32_bf16 v[14:17], v[180:183], v[204:207], v[14:17]
	v_mfma_f32_16x16x32_bf16 v[6:9], v[172:175], v[212:215], v[6:9]
	v_mfma_f32_16x16x32_bf16 v[2:5], v[180:183], v[212:215], v[2:5]
	s_barrier
	s_add_i32 s75, s75, 2
	s_add_u32 s20, s20, 0x100
	s_addc_u32 s21, s21, 0
	s_add_u32 s73, s73, 0x100
	s_addc_u32 s74, s74, 0
	s_cmp_gt_u32 s75, 13
	s_cbranch_scc1 .Lpp0_x
.LBB0_192:
	ds_read_b128 v[146:149], v152
	ds_read_b128 v[156:159], v152 offset:1024
	ds_read_b128 v[160:163], v152 offset:2048
	ds_read_b128 v[164:167], v152 offset:3072
	ds_read_b128 v[168:171], v153
	ds_read_b128 v[172:175], v153 offset:1024
	ds_read_b128 v[176:179], v153 offset:2048
	ds_read_b128 v[180:183], v153 offset:3072
	s_add_u32 s22, s20, 0xfffc0080
	s_addc_u32 s23, s21, -1
	s_cmp_eq_u32 s75, 12
	s_cselect_b32 s25, s5, s23
	s_cselect_b32 s24, s13, s22
	s_cselect_b32 s23, s11, s74
	s_cselect_b32 s22, s19, s73
	s_add_i32 m0, s27, 0xc000
	ds_read_b128 v[184:187], v154
	ds_read_b128 v[188:191], v154 offset:1024
	ds_read_b128 v[192:195], v154 offset:2048
	ds_read_b128 v[196:199], v154 offset:3072
	ds_read_b128 v[200:203], v154 offset:4096
	ds_read_b128 v[204:207], v154 offset:5120
	ds_read_b128 v[208:211], v154 offset:6144
	ds_read_b128 v[212:215], v154 offset:7168
	global_load_lds_dwordx4 v138, s[20:21]
	s_add_i32 m0, s27, 0xe000
	s_nop 0
	global_load_lds_dwordx4 v140, s[20:21]
	s_waitcnt vmcnt(8)
	s_waitcnt lgkmcnt(0)
	s_barrier
; #define PG8_STAGE(bufoff, gbase, voff) do { _Pragma("unroll") for (int _i = 0; _i < 2; ++_i) \
;         __builtin_amdgcn_global_load_lds((const unsigned*)((const char*)(gbase) + (voff)[_i]), (PG8_LAS unsigned*)(lds + (bufoff) + ldsw + _i * 8192), 16, 0, 0); } while (0)
; #define PG8_LDA(dst, b, h) do { _Pragma("unroll") for (int m = 0; m < 4; ++m) _Pragma("unroll") for (int k = 0; k < 2; ++k) dst[m][k] = *(const PG8_LAS bf16x8*)(lds + PG8_SA(b, h) + aoff + m * 2048 + k * 1024); } while (0)
; #define PG8_MMA(ai, bj, At, Bt) do { __builtin_amdgcn_s_setprio(1); _Pragma("unroll") for (int m = 0; m < 4; ++m) _Pragma("unroll") for (int n = 0; n < 2; ++n) _Pragma("unroll") for (int k = 0; k < 2; ++k) \
;         acc[ai][bj][m][n] = __builtin_amdgcn_mfma_f32_16x16x32_bf16(Bt[n][k], At[m][k], acc[ai][bj][m][n], 0, 0, 0); __builtin_amdgcn_s_setprio(0); } while (0)
; #define PG8_WAIT_V(n) asm volatile("s_waitcnt vmcnt(" #n ")" ::: "memory")
; #define PG8_WAIT_L(n) asm volatile("s_waitcnt lgkmcnt(" #n ")" ::: "memory")
; #define PG8_BAR __builtin_amdgcn_s_barrier()
; #define PG8_SCHED __builtin_amdgcn_sched_barrier(0)
; template <class Epi, class Sched, bool ALIGN_EPI = false, bool SP2 = false>
; __device__ __forceinline__ void gemm_phase(PG8_LAS unsigned char* lds, const Gemm g, const Sched& S, const Epi& E) {
;     ...
;             PG8_WAIT_V(8); PG8_WAIT_L(0); PG8_BAR; PG8_MMA(0, 0, At, B0); PG8_MMA(0, 1, At, B1); PG8_BAR; PG8_SCHED;
;             PG8_LDA(At, 0, 1); PG8_STAGE(PG8_SB(0, 0), b2, voffB); PG8_STAGE(PG8_SB(0, 1), b2 + hstepB, voffB); PG8_STAGE(PG8_SA(0, 0), a2, voffA);
;             PG8_WAIT_V(8); PG8_WAIT_L(0); PG8_BAR; PG8_MMA(1, 0, At, B0); PG8_MMA(1, 1, At, B1); PG8_BAR; PG8_SCHED;
	v_mfma_f32_16x16x32_bf16 v[126:129], v[146:149], v[184:187], v[126:129]
	v_mfma_f32_16x16x32_bf16 v[122:125], v[160:163], v[184:187], v[122:125]
	v_mfma_f32_16x16x32_bf16 v[114:117], v[146:149], v[192:195], v[114:117]
	v_mfma_f32_16x16x32_bf16 v[106:109], v[160:163], v[192:195], v[106:109]
	v_mfma_f32_16x16x32_bf16 v[98:101], v[146:149], v[200:203], v[98:101]
	v_mfma_f32_16x16x32_bf16 v[90:93], v[160:163], v[200:203], v[90:93]
	v_mfma_f32_16x16x32_bf16 v[82:85], v[146:149], v[208:211], v[82:85]
	v_mfma_f32_16x16x32_bf16 v[74:77], v[160:163], v[208:211], v[74:77]
	v_mfma_f32_16x16x32_bf16 v[126:129], v[156:159], v[188:191], v[126:129]
	v_mfma_f32_16x16x32_bf16 v[122:125], v[164:167], v[188:191], v[122:125]
	v_mfma_f32_16x16x32_bf16 v[114:117], v[156:159], v[196:199], v[114:117]
	v_mfma_f32_16x16x32_bf16 v[106:109], v[164:167], v[196:199], v[106:109]
	v_mfma_f32_16x16x32_bf16 v[98:101], v[156:159], v[204:207], v[98:101]
	v_mfma_f32_16x16x32_bf16 v[90:93], v[164:167], v[204:207], v[90:93]
	v_mfma_f32_16x16x32_bf16 v[82:85], v[156:159], v[212:215], v[82:85]
	v_mfma_f32_16x16x32_bf16 v[74:77], v[164:167], v[212:215], v[74:77]
	v_mfma_f32_16x16x32_bf16 v[118:121], v[168:171], v[184:187], v[118:121]
	v_mfma_f32_16x16x32_bf16 v[110:113], v[176:179], v[184:187], v[110:113]
	v_mfma_f32_16x16x32_bf16 v[102:105], v[168:171], v[192:195], v[102:105]
	v_mfma_f32_16x16x32_bf16 v[94:97], v[176:179], v[192:195], v[94:97]
	v_mfma_f32_16x16x32_bf16 v[86:89], v[168:171], v[200:203], v[86:89]
	v_mfma_f32_16x16x32_bf16 v[78:81], v[176:179], v[200:203], v[78:81]
	v_mfma_f32_16x16x32_bf16 v[70:73], v[168:171], v[208:211], v[70:73]
	v_mfma_f32_16x16x32_bf16 v[66:69], v[176:179], v[208:211], v[66:69]
	v_mfma_f32_16x16x32_bf16 v[118:121], v[172:175], v[188:191], v[118:121]
	v_mfma_f32_16x16x32_bf16 v[110:113], v[180:183], v[188:191], v[110:113]
	v_mfma_f32_16x16x32_bf16 v[102:105], v[172:175], v[196:199], v[102:105]
	v_mfma_f32_16x16x32_bf16 v[94:97], v[180:183], v[196:199], v[94:97]
	v_mfma_f32_16x16x32_bf16 v[86:89], v[172:175], v[204:207], v[86:89]
	v_mfma_f32_16x16x32_bf16 v[78:81], v[180:183], v[204:207], v[78:81]
	v_mfma_f32_16x16x32_bf16 v[70:73], v[172:175], v[212:215], v[70:73]
	v_mfma_f32_16x16x32_bf16 v[66:69], v[180:183], v[212:215], v[66:69]
	s_barrier
	s_add_i32 s76, s69, s26
	v_lshl_add_u64 v[216:217], s[22:23], 0, v[132:133]
	s_mov_b32 m0, s76
	ds_read_b128 v[184:187], v154 offset:16384
	ds_read_b128 v[188:191], v154 offset:17408
	ds_read_b128 v[192:195], v154 offset:18432
	ds_read_b128 v[196:199], v154 offset:19456
	ds_read_b128 v[200:203], v154 offset:20480
	ds_read_b128 v[204:207], v154 offset:21504
	ds_read_b128 v[208:211], v154 offset:22528
	ds_read_b128 v[212:215], v154 offset:23552
	global_load_lds_dwordx4 v132, s[22:23]
	s_add_i32 m0, s76, 0x2000
	s_add_u32 s76, s22, 0x10000
	v_lshl_add_u64 v[218:219], s[22:23], 0, v[136:137]
	s_addc_u32 s77, s23, 0
	s_add_i32 s78, s70, s26
	global_load_lds_dwordx4 v136, s[22:23]
	s_mov_b32 m0, s78
	v_lshl_add_u64 v[222:223], s[24:25], 0, v[134:135]
	global_load_lds_dwordx4 v132, s[76:77]
	s_add_i32 m0, s78, 0x2000
	s_nop 0
	global_load_lds_dwordx4 v136, s[76:77]
	v_lshl_add_u64 v[220:221], s[24:25], 0, v[130:131]
	s_mov_b32 m0, s27
	s_nop 0
	global_load_lds_dwordx4 v130, s[24:25]
	s_mov_b32 m0, s28
	s_nop 0
	global_load_lds_dwordx4 v134, s[24:25]
	s_waitcnt vmcnt(8)
	s_waitcnt lgkmcnt(0)
	s_barrier
	v_mfma_f32_16x16x32_bf16 v[62:65], v[146:149], v[184:187], v[62:65]
	v_mfma_f32_16x16x32_bf16 v[58:61], v[160:163], v[184:187], v[58:61]
	v_mfma_f32_16x16x32_bf16 v[50:53], v[146:149], v[192:195], v[50:53]
	v_mfma_f32_16x16x32_bf16 v[42:45], v[160:163], v[192:195], v[42:45]
	v_mfma_f32_16x16x32_bf16 v[34:37], v[146:149], v[200:203], v[34:37]
	v_mfma_f32_16x16x32_bf16 v[26:29], v[160:163], v[200:203], v[26:29]
	v_mfma_f32_16x16x32_bf16 v[18:21], v[146:149], v[208:211], v[18:21]
	v_mfma_f32_16x16x32_bf16 v[10:13], v[160:163], v[208:211], v[10:13]
	v_mfma_f32_16x16x32_bf16 v[62:65], v[156:159], v[188:191], v[62:65]
	v_mfma_f32_16x16x32_bf16 v[58:61], v[164:167], v[188:191], v[58:61]
	v_mfma_f32_16x16x32_bf16 v[50:53], v[156:159], v[196:199], v[50:53]
	v_mfma_f32_16x16x32_bf16 v[42:45], v[164:167], v[196:199], v[42:45]
	v_mfma_f32_16x16x32_bf16 v[34:37], v[156:159], v[204:207], v[34:37]
	v_mfma_f32_16x16x32_bf16 v[26:29], v[164:167], v[204:207], v[26:29]
	v_mfma_f32_16x16x32_bf16 v[18:21], v[156:159], v[212:215], v[18:21]
	v_mfma_f32_16x16x32_bf16 v[10:13], v[164:167], v[212:215], v[10:13]
	v_mfma_f32_16x16x32_bf16 v[54:57], v[168:171], v[184:187], v[54:57]
	v_mfma_f32_16x16x32_bf16 v[46:49], v[176:179], v[184:187], v[46:49]
	v_mfma_f32_16x16x32_bf16 v[38:41], v[168:171], v[192:195], v[38:41]
	v_mfma_f32_16x16x32_bf16 v[30:33], v[176:179], v[192:195], v[30:33]
	v_mfma_f32_16x16x32_bf16 v[22:25], v[168:171], v[200:203], v[22:25]
	v_mfma_f32_16x16x32_bf16 v[14:17], v[176:179], v[200:203], v[14:17]
	v_mfma_f32_16x16x32_bf16 v[6:9], v[168:171], v[208:211], v[6:9]
	v_mfma_f32_16x16x32_bf16 v[2:5], v[176:179], v[208:211], v[2:5]
	v_mfma_f32_16x16x32_bf16 v[54:57], v[172:175], v[188:191], v[54:57]
	v_mfma_f32_16x16x32_bf16 v[46:49], v[180:183], v[188:191], v[46:49]
	v_mfma_f32_16x16x32_bf16 v[38:41], v[172:175], v[196:199], v[38:41]
	v_mfma_f32_16x16x32_bf16 v[30:33], v[180:183], v[196:199], v[30:33]
	v_mfma_f32_16x16x32_bf16 v[22:25], v[172:175], v[204:207], v[22:25]
	v_mfma_f32_16x16x32_bf16 v[14:17], v[180:183], v[204:207], v[14:17]
	v_mfma_f32_16x16x32_bf16 v[6:9], v[172:175], v[212:215], v[6:9]
	v_mfma_f32_16x16x32_bf16 v[2:5], v[180:183], v[212:215], v[2:5]
	s_barrier
; #define PG8_STAGE(bufoff, gbase, voff) do { _Pragma("unroll") for (int _i = 0; _i < 2; ++_i) \
;         __builtin_amdgcn_global_load_lds((const unsigned*)((const char*)(gbase) + (voff)[_i]), (PG8_LAS unsigned*)(lds + (bufoff) + ldsw + _i * 8192), 16, 0, 0); } while (0)
; #define PG8_LDA(dst, b, h) do { _Pragma("unroll") for (int m = 0; m < 4; ++m) _Pragma("unroll") for (int k = 0; k < 2; ++k) dst[m][k] = *(const PG8_LAS bf16x8*)(lds + PG8_SA(b, h) + aoff + m * 2048 + k * 1024); } while (0)
; #define PG8_LDB(dst, b, h) do { _Pragma("unroll") for (int n = 0; n < 2; ++n) _Pragma("unroll") for (int k = 0; k < 2; ++k) dst[n][k] = *(const PG8_LAS bf16x8*)(lds + PG8_SB(b, h) + boff + n * 2048 + k * 1024); } while (0)
; #define PG8_MMA(ai, bj, At, Bt) do { __builtin_amdgcn_s_setprio(1); _Pragma("unroll") for (int m = 0; m < 4; ++m) _Pragma("unroll") for (int n = 0; n < 2; ++n) _Pragma("unroll") for (int k = 0; k < 2; ++k) \
;         acc[ai][bj][m][n] = __builtin_amdgcn_mfma_f32_16x16x32_bf16(Bt[n][k], At[m][k], acc[ai][bj][m][n], 0, 0, 0); __builtin_amdgcn_s_setprio(0); } while (0)
; #define PG8_WAIT_V(n) asm volatile("s_waitcnt vmcnt(" #n ")" ::: "memory")
; #define PG8_WAIT_L(n) asm volatile("s_waitcnt lgkmcnt(" #n ")" ::: "memory")
; #define PG8_BAR __builtin_amdgcn_s_barrier()
; #define PG8_SCHED __builtin_amdgcn_sched_barrier(0)
; template <class Epi, class Sched, bool ALIGN_EPI = false, bool SP2 = false>
; __device__ __forceinline__ void gemm_phase(PG8_LAS unsigned char* lds, const Gemm g, const Sched& S, const Epi& E) {
;     ...
;             PG8_LDB(B0, 1, 0); PG8_LDB(B1, 1, 1); PG8_SCHED; PG8_LDA(At, 1, 0); PG8_STAGE(PG8_SA(0, 1), a2 + hstep, voffA);
;             PG8_WAIT_V(8); PG8_WAIT_L(0); PG8_BAR; PG8_MMA(0, 0, At, B0); PG8_MMA(0, 1, At, B1); PG8_BAR; PG8_SCHED;
;             PG8_LDA(At, 1, 1); PG8_STAGE(PG8_SB(1, 0), b3, voffB); PG8_STAGE(PG8_SB(1, 1), b3 + hstepB, voffB); PG8_STAGE(PG8_SA(1, 0), a3, voffA);
;             PG8_WAIT_V(8); PG8_WAIT_L(0); PG8_BAR; PG8_MMA(1, 0, At, B0); PG8_MMA(1, 1, At, B1); PG8_BAR; PG8_SCHED;
	s_add_i32 s76, 0, 0x18000
	v_add_u32_e32 v155, s76, v150
	s_add_i32 s77, 0, 0x1c000
	ds_read_b128 v[146:149], v155
	ds_read_b128 v[156:159], v155 offset:1024
	ds_read_b128 v[160:163], v155 offset:2048
	ds_read_b128 v[164:167], v155 offset:3072
	v_add_u32_e32 v155, s77, v150
	ds_read_b128 v[168:171], v155
	ds_read_b128 v[172:175], v155 offset:1024
	ds_read_b128 v[176:179], v155 offset:2048
	ds_read_b128 v[180:183], v155 offset:3072
	s_add_u32 s24, s24, 0x40000
	s_addc_u32 s25, s25, 0
	s_mov_b32 m0, s29
	ds_read_b128 v[184:187], v154 offset:32768
	ds_read_b128 v[188:191], v154 offset:33792
	ds_read_b128 v[192:195], v154 offset:34816
	ds_read_b128 v[196:199], v154 offset:35840
	ds_read_b128 v[200:203], v154 offset:36864
	ds_read_b128 v[204:207], v154 offset:37888
	ds_read_b128 v[208:211], v154 offset:38912
	ds_read_b128 v[212:215], v154 offset:39936
	global_load_lds_dwordx4 v130, s[24:25]
	s_mov_b32 m0, s30
	s_nop 0
	global_load_lds_dwordx4 v134, s[24:25]
	s_waitcnt vmcnt(8)
	s_waitcnt lgkmcnt(0)
	s_barrier
	v_mfma_f32_16x16x32_bf16 v[126:129], v[146:149], v[184:187], v[126:129]
	v_mfma_f32_16x16x32_bf16 v[122:125], v[160:163], v[184:187], v[122:125]
	v_mfma_f32_16x16x32_bf16 v[114:117], v[146:149], v[192:195], v[114:117]
	v_mfma_f32_16x16x32_bf16 v[106:109], v[160:163], v[192:195], v[106:109]
	v_mfma_f32_16x16x32_bf16 v[98:101], v[146:149], v[200:203], v[98:101]
	v_mfma_f32_16x16x32_bf16 v[90:93], v[160:163], v[200:203], v[90:93]
	v_mfma_f32_16x16x32_bf16 v[82:85], v[146:149], v[208:211], v[82:85]
	v_mfma_f32_16x16x32_bf16 v[74:77], v[160:163], v[208:211], v[74:77]
	v_mfma_f32_16x16x32_bf16 v[126:129], v[156:159], v[188:191], v[126:129]
	v_mfma_f32_16x16x32_bf16 v[122:125], v[164:167], v[188:191], v[122:125]
	v_mfma_f32_16x16x32_bf16 v[114:117], v[156:159], v[196:199], v[114:117]
	v_mfma_f32_16x16x32_bf16 v[106:109], v[164:167], v[196:199], v[106:109]
	v_mfma_f32_16x16x32_bf16 v[98:101], v[156:159], v[204:207], v[98:101]
	v_mfma_f32_16x16x32_bf16 v[90:93], v[164:167], v[204:207], v[90:93]
	v_mfma_f32_16x16x32_bf16 v[82:85], v[156:159], v[212:215], v[82:85]
	v_mfma_f32_16x16x32_bf16 v[74:77], v[164:167], v[212:215], v[74:77]
	v_mfma_f32_16x16x32_bf16 v[118:121], v[168:171], v[184:187], v[118:121]
	v_mfma_f32_16x16x32_bf16 v[110:113], v[176:179], v[184:187], v[110:113]
	v_mfma_f32_16x16x32_bf16 v[102:105], v[168:171], v[192:195], v[102:105]
	v_mfma_f32_16x16x32_bf16 v[94:97], v[176:179], v[192:195], v[94:97]
	v_mfma_f32_16x16x32_bf16 v[86:89], v[168:171], v[200:203], v[86:89]
	v_mfma_f32_16x16x32_bf16 v[78:81], v[176:179], v[200:203], v[78:81]
	v_mfma_f32_16x16x32_bf16 v[70:73], v[168:171], v[208:211], v[70:73]
	v_mfma_f32_16x16x32_bf16 v[66:69], v[176:179], v[208:211], v[66:69]
	v_mfma_f32_16x16x32_bf16 v[118:121], v[172:175], v[188:191], v[118:121]
	v_mfma_f32_16x16x32_bf16 v[110:113], v[180:183], v[188:191], v[110:113]
	v_mfma_f32_16x16x32_bf16 v[102:105], v[172:175], v[196:199], v[102:105]
	v_mfma_f32_16x16x32_bf16 v[94:97], v[180:183], v[196:199], v[94:97]
	v_mfma_f32_16x16x32_bf16 v[86:89], v[172:175], v[204:207], v[86:89]
	v_mfma_f32_16x16x32_bf16 v[78:81], v[180:183], v[204:207], v[78:81]
	v_mfma_f32_16x16x32_bf16 v[70:73], v[172:175], v[212:215], v[70:73]
	v_mfma_f32_16x16x32_bf16 v[66:69], v[180:183], v[212:215], v[66:69]
	s_barrier
	s_add_i32 s24, s76, s26
	v_lshl_add_u64 v[216:217], v[216:217], 0, s[6:7]
	s_mov_b32 m0, s24
	ds_read_b128 v[184:187], v154 offset:49152
	ds_read_b128 v[188:191], v154 offset:50176
	ds_read_b128 v[192:195], v154 offset:51200
	ds_read_b128 v[196:199], v154 offset:52224
	ds_read_b128 v[200:203], v154 offset:53248
	ds_read_b128 v[204:207], v154 offset:54272
	ds_read_b128 v[208:211], v154 offset:55296
	ds_read_b128 v[212:215], v154 offset:56320
	global_load_lds_dwordx4 v[216:217], off
	s_add_i32 m0, s24, 0x2000
	s_add_u32 s22, s22, 0x10080
	v_lshl_add_u64 v[216:217], v[218:219], 0, s[6:7]
	s_addc_u32 s23, s23, 0
	s_add_i32 s24, s77, s26
	global_load_lds_dwordx4 v[216:217], off
	s_mov_b32 m0, s24
	s_nop 0
	global_load_lds_dwordx4 v132, s[22:23]
	s_add_i32 m0, s24, 0x2000
	s_nop 0
	global_load_lds_dwordx4 v136, s[22:23]
	v_lshl_add_u64 v[216:217], v[220:221], 0, s[6:7]
	s_mov_b32 m0, s33
	s_nop 0
	global_load_lds_dwordx4 v[216:217], off
	v_lshl_add_u64 v[216:217], v[222:223], 0, s[6:7]
	s_mov_b32 m0, s34
	s_nop 0
	global_load_lds_dwordx4 v[216:217], off
	s_waitcnt vmcnt(8)
	s_waitcnt lgkmcnt(0)
	s_barrier
	v_mfma_f32_16x16x32_bf16 v[62:65], v[146:149], v[184:187], v[62:65]
	v_mfma_f32_16x16x32_bf16 v[58:61], v[160:163], v[184:187], v[58:61]
	v_mfma_f32_16x16x32_bf16 v[50:53], v[146:149], v[192:195], v[50:53]
	v_mfma_f32_16x16x32_bf16 v[42:45], v[160:163], v[192:195], v[42:45]
	v_mfma_f32_16x16x32_bf16 v[34:37], v[146:149], v[200:203], v[34:37]
	v_mfma_f32_16x16x32_bf16 v[26:29], v[160:163], v[200:203], v[26:29]
	v_mfma_f32_16x16x32_bf16 v[18:21], v[146:149], v[208:211], v[18:21]
	v_mfma_f32_16x16x32_bf16 v[10:13], v[160:163], v[208:211], v[10:13]
	v_mfma_f32_16x16x32_bf16 v[62:65], v[156:159], v[188:191], v[62:65]
	v_mfma_f32_16x16x32_bf16 v[58:61], v[164:167], v[188:191], v[58:61]
	v_mfma_f32_16x16x32_bf16 v[50:53], v[156:159], v[196:199], v[50:53]
	v_mfma_f32_16x16x32_bf16 v[42:45], v[164:167], v[196:199], v[42:45]
	v_mfma_f32_16x16x32_bf16 v[34:37], v[156:159], v[204:207], v[34:37]
	v_mfma_f32_16x16x32_bf16 v[26:29], v[164:167], v[204:207], v[26:29]
	v_mfma_f32_16x16x32_bf16 v[18:21], v[156:159], v[212:215], v[18:21]
	v_mfma_f32_16x16x32_bf16 v[10:13], v[164:167], v[212:215], v[10:13]
	v_mfma_f32_16x16x32_bf16 v[54:57], v[168:171], v[184:187], v[54:57]
	v_mfma_f32_16x16x32_bf16 v[46:49], v[176:179], v[184:187], v[46:49]
	v_mfma_f32_16x16x32_bf16 v[38:41], v[168:171], v[192:195], v[38:41]
	v_mfma_f32_16x16x32_bf16 v[30:33], v[176:179], v[192:195], v[30:33]
	v_mfma_f32_16x16x32_bf16 v[22:25], v[168:171], v[200:203], v[22:25]
	v_mfma_f32_16x16x32_bf16 v[14:17], v[176:179], v[200:203], v[14:17]
	v_mfma_f32_16x16x32_bf16 v[6:9], v[168:171], v[208:211], v[6:9]
	v_mfma_f32_16x16x32_bf16 v[2:5], v[176:179], v[208:211], v[2:5]
	v_mfma_f32_16x16x32_bf16 v[54:57], v[172:175], v[188:191], v[54:57]
	v_mfma_f32_16x16x32_bf16 v[46:49], v[180:183], v[188:191], v[46:49]
	v_mfma_f32_16x16x32_bf16 v[38:41], v[172:175], v[196:199], v[38:41]
	v_mfma_f32_16x16x32_bf16 v[30:33], v[180:183], v[196:199], v[30:33]
	v_mfma_f32_16x16x32_bf16 v[22:25], v[172:175], v[204:207], v[22:25]
	v_mfma_f32_16x16x32_bf16 v[14:17], v[180:183], v[204:207], v[14:17]
	v_mfma_f32_16x16x32_bf16 v[6:9], v[172:175], v[212:215], v[6:9]
	v_mfma_f32_16x16x32_bf16 v[2:5], v[180:183], v[212:215], v[2:5]
	s_barrier
	s_add_i32 s75, s75, 2
	s_add_u32 s20, s20, 0x100
	s_addc_u32 s21, s21, 0
	s_add_u32 s73, s73, 0x100
	s_addc_u32 s74, s74, 0
	s_cmp_gt_u32 s75, 13
	s_cbranch_scc0 .LBB0_192

; #define PG8_STAGE(bufoff, gbase, voff) do { _Pragma("unroll") for (int _i = 0; _i < 2; ++_i) \
;         __builtin_amdgcn_global_load_lds((const unsigned*)((const char*)(gbase) + (voff)[_i]), (PG8_LAS unsigned*)(lds + (bufoff) + ldsw + _i * 8192), 16, 0, 0); } while (0)
; #define PG8_LDA(dst, b, h) do { _Pragma("unroll") for (int m = 0; m < 4; ++m) _Pragma("unroll") for (int k = 0; k < 2; ++k) dst[m][k] = *(const PG8_LAS bf16x8*)(lds + PG8_SA(b, h) + aoff + m * 2048 + k * 1024); } while (0)
; #define PG8_LDB(dst, b, h) do { _Pragma("unroll") for (int n = 0; n < 2; ++n) _Pragma("unroll") for (int k = 0; k < 2; ++k) dst[n][k] = *(const PG8_LAS bf16x8*)(lds + PG8_SB(b, h) + boff + n * 2048 + k * 1024); } while (0)
; #define PG8_WAIT_V(n) asm volatile("s_waitcnt vmcnt(" #n ")" ::: "memory")
; #define PG8_WAIT_L(n) asm volatile("s_waitcnt lgkmcnt(" #n ")" ::: "memory")
; #define PG8_BAR __builtin_amdgcn_s_barrier()
; #define PG8_SCHED __builtin_amdgcn_sched_barrier(0)
; template <class Epi, class Sched, bool ALIGN_EPI = false, bool SP2 = false>
; __device__ __forceinline__ void gemm_phase(PG8_LAS unsigned char* lds, const Gemm g, const Sched& S, const Epi& E) {
;     ...
;         const char* nA = has_next ? (const char*)g.A + (size_t)nxt.pm * tstep : cA; const char* nB = has_next ? (const char*)g.Bt + (size_t)nxt.pn * tstep : cB;
;         for (int t = 0; t < nt; t += 2) {
;             if constexpr (Epi::HAS_MID) { if (t == nt / 2) E.mid(acc, cur, wr, wc, fr, fq); }
;             const bool last = (t == nt - 2);
;             const char* a1 = cA + (size_t)(t + 1) * kstep;
;             const char* a2 = last ? nA : cA + (size_t)(t + 2) * kstep; const char* b2 = last ? nB : cB + (size_t)(t + 2) * kstep;
;             const char* a3 = a2 + kstep; const char* b3 = b2 + kstep;
;             if (last && has_next) S.a_ready(nxt);
;             if constexpr (SP2) {
;             PG8_LDB(B0, 0, 0); PG8_LDB(B1, 0, 1); PG8_SCHED; PG8_LDA(At, 0, 0); PG8_STAGE(PG8_SA(1, 1), a1 + hstep, voffA);
;             PG8_WAIT_V(8); PG8_WAIT_L(0); PG8_BAR; PG8_MMA(0, 0, At, B0); PG8_MMA(0, 1, At, B1); PG8_BAR; PG8_SCHED;
;             PG8_LDA(At, 0, 1); PG8_STAGE(PG8_SB(0, 0), b2, voffB); PG8_STAGE(PG8_SB(0, 1), b2 + hstepB, voffB); PG8_STAGE(PG8_SA(0, 0), a2, voffA);
;             PG8_WAIT_V(8); PG8_WAIT_L(0); PG8_BAR; PG8_MMA(1, 0, At, B0); PG8_MMA(1, 1, At, B1); PG8_BAR; PG8_SCHED;
.LBB0_1312:
	s_ashr_i32 s27, s26, 31
	s_lshl_b64 s[28:29], s[26:27], 19
	s_add_u32 s28, s12, s28
	s_addc_u32 s29, s13, s29
	s_and_b64 s[34:35], s[6:7], exec
	s_cselect_b32 s9, s29, s39
	s_cselect_b32 s27, s28, s38
	s_ashr_i32 s25, s24, 31
	s_lshl_b64 s[34:35], s[24:25], 19
	s_add_u32 s34, s78, s34
	s_addc_u32 s35, s79, s35
	s_and_b64 s[42:43], s[6:7], exec
	s_cselect_b32 s25, s35, s41
	s_cselect_b32 s37, s34, s40
	s_add_u32 s38, s38, 0x40080
	s_addc_u32 s39, s39, 0
	s_add_u32 s59, s40, 0x100
	s_addc_u32 s60, s41, 0
	s_mov_b32 s61, -2
	ds_read_b128 v[146:149], v154
	ds_read_b128 v[158:161], v154 offset:1024
	ds_read_b128 v[162:165], v154 offset:2048
	ds_read_b128 v[166:169], v154 offset:3072
	ds_read_b128 v[170:173], v155
	ds_read_b128 v[174:177], v155 offset:1024
	ds_read_b128 v[178:181], v155 offset:2048
	ds_read_b128 v[182:185], v155 offset:3072
	s_add_u32 s40, s38, 0xfffc0080
	s_addc_u32 s41, s39, -1
	s_cmp_eq_u32 s61, 12
	s_cselect_b32 s43, s9, s41
	s_cselect_b32 s42, s27, s40
	s_cselect_b32 s41, s25, s60
	s_cselect_b32 s40, s37, s59
	s_add_i32 m0, s31, 0xc000
	ds_read_b128 v[186:189], v156
	ds_read_b128 v[190:193], v156 offset:1024
	ds_read_b128 v[194:197], v156 offset:2048
	ds_read_b128 v[198:201], v156 offset:3072
	ds_read_b128 v[202:205], v156 offset:4096
	ds_read_b128 v[206:209], v156 offset:5120
	ds_read_b128 v[210:213], v156 offset:6144
	ds_read_b128 v[214:217], v156 offset:7168
	global_load_lds_dwordx4 v138, s[38:39]
	s_add_i32 m0, s31, 0xe000
	s_nop 0
	global_load_lds_dwordx4 v140, s[38:39]
	s_waitcnt vmcnt(8)
	s_waitcnt lgkmcnt(0)
	s_barrier
	v_mfma_f32_16x16x32_bf16 v[126:129], v[146:149], v[186:189], 0
	v_mfma_f32_16x16x32_bf16 v[122:125], v[162:165], v[186:189], 0
	v_mfma_f32_16x16x32_bf16 v[110:113], v[146:149], v[194:197], 0
	v_mfma_f32_16x16x32_bf16 v[106:109], v[162:165], v[194:197], 0
	v_mfma_f32_16x16x32_bf16 v[94:97], v[146:149], v[202:205], 0
	v_mfma_f32_16x16x32_bf16 v[90:93], v[162:165], v[202:205], 0
	v_mfma_f32_16x16x32_bf16 v[78:81], v[146:149], v[210:213], 0
	v_mfma_f32_16x16x32_bf16 v[74:77], v[162:165], v[210:213], 0
	v_mfma_f32_16x16x32_bf16 v[126:129], v[158:161], v[190:193], v[126:129]
	v_mfma_f32_16x16x32_bf16 v[122:125], v[166:169], v[190:193], v[122:125]
	v_mfma_f32_16x16x32_bf16 v[110:113], v[158:161], v[198:201], v[110:113]
	v_mfma_f32_16x16x32_bf16 v[106:109], v[166:169], v[198:201], v[106:109]
	v_mfma_f32_16x16x32_bf16 v[94:97], v[158:161], v[206:209], v[94:97]
	v_mfma_f32_16x16x32_bf16 v[90:93], v[166:169], v[206:209], v[90:93]
	v_mfma_f32_16x16x32_bf16 v[78:81], v[158:161], v[214:217], v[78:81]
	v_mfma_f32_16x16x32_bf16 v[74:77], v[166:169], v[214:217], v[74:77]
	v_mfma_f32_16x16x32_bf16 v[118:121], v[170:173], v[186:189], 0
	v_mfma_f32_16x16x32_bf16 v[114:117], v[178:181], v[186:189], 0
	v_mfma_f32_16x16x32_bf16 v[102:105], v[170:173], v[194:197], 0
	v_mfma_f32_16x16x32_bf16 v[98:101], v[178:181], v[194:197], 0
	v_mfma_f32_16x16x32_bf16 v[86:89], v[170:173], v[202:205], 0
	v_mfma_f32_16x16x32_bf16 v[82:85], v[178:181], v[202:205], 0
	v_mfma_f32_16x16x32_bf16 v[70:73], v[170:173], v[210:213], 0
	v_mfma_f32_16x16x32_bf16 v[66:69], v[178:181], v[210:213], 0
	v_mfma_f32_16x16x32_bf16 v[118:121], v[174:177], v[190:193], v[118:121]
	v_mfma_f32_16x16x32_bf16 v[114:117], v[182:185], v[190:193], v[114:117]
	v_mfma_f32_16x16x32_bf16 v[102:105], v[174:177], v[198:201], v[102:105]
	v_mfma_f32_16x16x32_bf16 v[98:101], v[182:185], v[198:201], v[98:101]
	v_mfma_f32_16x16x32_bf16 v[86:89], v[174:177], v[206:209], v[86:89]
	v_mfma_f32_16x16x32_bf16 v[82:85], v[182:185], v[206:209], v[82:85]
	v_mfma_f32_16x16x32_bf16 v[70:73], v[174:177], v[214:217], v[70:73]
	v_mfma_f32_16x16x32_bf16 v[66:69], v[182:185], v[214:217], v[66:69]
	s_barrier
	s_add_i32 s62, s57, s30
	v_lshl_add_u64 v[150:151], s[40:41], 0, v[132:133]
	s_mov_b32 m0, s62
	ds_read_b128 v[186:189], v156 offset:16384
	ds_read_b128 v[190:193], v156 offset:17408
	ds_read_b128 v[194:197], v156 offset:18432
	ds_read_b128 v[198:201], v156 offset:19456
	ds_read_b128 v[202:205], v156 offset:20480
	ds_read_b128 v[206:209], v156 offset:21504
	ds_read_b128 v[210:213], v156 offset:22528
	ds_read_b128 v[214:217], v156 offset:23552
	global_load_lds_dwordx4 v132, s[40:41]
	s_add_i32 m0, s62, 0x2000
	s_add_u32 s62, s40, 0x10000
	v_lshl_add_u64 v[218:219], s[40:41], 0, v[136:137]
	s_addc_u32 s63, s41, 0
	s_add_i32 s64, s58, s30
	global_load_lds_dwordx4 v136, s[40:41]
	s_mov_b32 m0, s64
	v_lshl_add_u64 v[222:223], s[42:43], 0, v[134:135]
	global_load_lds_dwordx4 v132, s[62:63]
	s_add_i32 m0, s64, 0x2000
	s_nop 0
	global_load_lds_dwordx4 v136, s[62:63]
	v_lshl_add_u64 v[220:221], s[42:43], 0, v[130:131]
	s_mov_b32 m0, s31
	s_nop 0
	global_load_lds_dwordx4 v130, s[42:43]
	s_mov_b32 m0, s33
	s_nop 0
	global_load_lds_dwordx4 v134, s[42:43]
	s_waitcnt vmcnt(8)
	s_waitcnt lgkmcnt(0)
	s_barrier
; #define PG8_STAGE(bufoff, gbase, voff) do { _Pragma("unroll") for (int _i = 0; _i < 2; ++_i) \
;         __builtin_amdgcn_global_load_lds((const unsigned*)((const char*)(gbase) + (voff)[_i]), (PG8_LAS unsigned*)(lds + (bufoff) + ldsw + _i * 8192), 16, 0, 0); } while (0)
; #define PG8_LDA(dst, b, h) do { _Pragma("unroll") for (int m = 0; m < 4; ++m) _Pragma("unroll") for (int k = 0; k < 2; ++k) dst[m][k] = *(const PG8_LAS bf16x8*)(lds + PG8_SA(b, h) + aoff + m * 2048 + k * 1024); } while (0)
; #define PG8_LDB(dst, b, h) do { _Pragma("unroll") for (int n = 0; n < 2; ++n) _Pragma("unroll") for (int k = 0; k < 2; ++k) dst[n][k] = *(const PG8_LAS bf16x8*)(lds + PG8_SB(b, h) + boff + n * 2048 + k * 1024); } while (0)
; #define PG8_MMA(ai, bj, At, Bt) do { __builtin_amdgcn_s_setprio(1); _Pragma("unroll") for (int m = 0; m < 4; ++m) _Pragma("unroll") for (int n = 0; n < 2; ++n) _Pragma("unroll") for (int k = 0; k < 2; ++k) \
;         acc[ai][bj][m][n] = __builtin_amdgcn_mfma_f32_16x16x32_bf16(Bt[n][k], At[m][k], acc[ai][bj][m][n], 0, 0, 0); __builtin_amdgcn_s_setprio(0); } while (0)
; #define PG8_WAIT_V(n) asm volatile("s_waitcnt vmcnt(" #n ")" ::: "memory")
; #define PG8_WAIT_L(n) asm volatile("s_waitcnt lgkmcnt(" #n ")" ::: "memory")
; #define PG8_BAR __builtin_amdgcn_s_barrier()
; #define PG8_SCHED __builtin_amdgcn_sched_barrier(0)
; template <class Epi, class Sched, bool ALIGN_EPI = false, bool SP2 = false>
; __device__ __forceinline__ void gemm_phase(PG8_LAS unsigned char* lds, const Gemm g, const Sched& S, const Epi& E) {
;     ...
;             PG8_WAIT_V(8); PG8_WAIT_L(0); PG8_BAR; PG8_MMA(1, 0, At, B0); PG8_MMA(1, 1, At, B1); PG8_BAR; PG8_SCHED;
;             PG8_LDB(B0, 1, 0); PG8_LDB(B1, 1, 1); PG8_SCHED; PG8_LDA(At, 1, 0); PG8_STAGE(PG8_SA(0, 1), a2 + hstep, voffA);
;             PG8_WAIT_V(8); PG8_WAIT_L(0); PG8_BAR; PG8_MMA(0, 0, At, B0); PG8_MMA(0, 1, At, B1); PG8_BAR; PG8_SCHED;
	v_mfma_f32_16x16x32_bf16 v[62:65], v[146:149], v[186:189], 0
	v_mfma_f32_16x16x32_bf16 v[58:61], v[162:165], v[186:189], 0
	v_mfma_f32_16x16x32_bf16 v[46:49], v[146:149], v[194:197], 0
	v_mfma_f32_16x16x32_bf16 v[42:45], v[162:165], v[194:197], 0
	v_mfma_f32_16x16x32_bf16 v[30:33], v[146:149], v[202:205], 0
	v_mfma_f32_16x16x32_bf16 v[26:29], v[162:165], v[202:205], 0
	v_mfma_f32_16x16x32_bf16 v[14:17], v[146:149], v[210:213], 0
	v_mfma_f32_16x16x32_bf16 v[10:13], v[162:165], v[210:213], 0
	v_mfma_f32_16x16x32_bf16 v[62:65], v[158:161], v[190:193], v[62:65]
	v_mfma_f32_16x16x32_bf16 v[58:61], v[166:169], v[190:193], v[58:61]
	v_mfma_f32_16x16x32_bf16 v[46:49], v[158:161], v[198:201], v[46:49]
	v_mfma_f32_16x16x32_bf16 v[42:45], v[166:169], v[198:201], v[42:45]
	v_mfma_f32_16x16x32_bf16 v[30:33], v[158:161], v[206:209], v[30:33]
	v_mfma_f32_16x16x32_bf16 v[26:29], v[166:169], v[206:209], v[26:29]
	v_mfma_f32_16x16x32_bf16 v[14:17], v[158:161], v[214:217], v[14:17]
	v_mfma_f32_16x16x32_bf16 v[10:13], v[166:169], v[214:217], v[10:13]
	v_mfma_f32_16x16x32_bf16 v[54:57], v[170:173], v[186:189], 0
	v_mfma_f32_16x16x32_bf16 v[50:53], v[178:181], v[186:189], 0
	v_mfma_f32_16x16x32_bf16 v[38:41], v[170:173], v[194:197], 0
	v_mfma_f32_16x16x32_bf16 v[34:37], v[178:181], v[194:197], 0
	v_mfma_f32_16x16x32_bf16 v[22:25], v[170:173], v[202:205], 0
	v_mfma_f32_16x16x32_bf16 v[18:21], v[178:181], v[202:205], 0
	v_mfma_f32_16x16x32_bf16 v[6:9], v[170:173], v[210:213], 0
	v_mfma_f32_16x16x32_bf16 v[2:5], v[178:181], v[210:213], 0
	v_mfma_f32_16x16x32_bf16 v[54:57], v[174:177], v[190:193], v[54:57]
	v_mfma_f32_16x16x32_bf16 v[50:53], v[182:185], v[190:193], v[50:53]
	v_mfma_f32_16x16x32_bf16 v[38:41], v[174:177], v[198:201], v[38:41]
	v_mfma_f32_16x16x32_bf16 v[34:37], v[182:185], v[198:201], v[34:37]
	v_mfma_f32_16x16x32_bf16 v[22:25], v[174:177], v[206:209], v[22:25]
	v_mfma_f32_16x16x32_bf16 v[18:21], v[182:185], v[206:209], v[18:21]
	v_mfma_f32_16x16x32_bf16 v[6:9], v[174:177], v[214:217], v[6:9]
	v_mfma_f32_16x16x32_bf16 v[2:5], v[182:185], v[214:217], v[2:5]
	s_barrier
	s_add_i32 s62, 0, 0x18000
	v_add_u32_e32 v157, s62, v152
	s_add_i32 s63, 0, 0x1c000
	ds_read_b128 v[146:149], v157
	ds_read_b128 v[158:161], v157 offset:1024
	ds_read_b128 v[162:165], v157 offset:2048
	ds_read_b128 v[166:169], v157 offset:3072
	v_add_u32_e32 v157, s63, v152
	ds_read_b128 v[170:173], v157
	ds_read_b128 v[174:177], v157 offset:1024
	ds_read_b128 v[178:181], v157 offset:2048
	ds_read_b128 v[182:185], v157 offset:3072
	s_add_u32 s42, s42, 0x40000
	s_addc_u32 s43, s43, 0
	s_mov_b32 m0, s44
	ds_read_b128 v[186:189], v156 offset:32768
	ds_read_b128 v[190:193], v156 offset:33792
	ds_read_b128 v[194:197], v156 offset:34816
	ds_read_b128 v[198:201], v156 offset:35840
	ds_read_b128 v[202:205], v156 offset:36864
	ds_read_b128 v[206:209], v156 offset:37888
	ds_read_b128 v[210:213], v156 offset:38912
	ds_read_b128 v[214:217], v156 offset:39936
	global_load_lds_dwordx4 v130, s[42:43]
	s_mov_b32 m0, s45
	s_nop 0
	global_load_lds_dwordx4 v134, s[42:43]
	s_waitcnt vmcnt(8)
	s_waitcnt lgkmcnt(0)
	s_barrier
	v_mfma_f32_16x16x32_bf16 v[126:129], v[146:149], v[186:189], v[126:129]
	v_mfma_f32_16x16x32_bf16 v[122:125], v[162:165], v[186:189], v[122:125]
	v_mfma_f32_16x16x32_bf16 v[110:113], v[146:149], v[194:197], v[110:113]
	v_mfma_f32_16x16x32_bf16 v[106:109], v[162:165], v[194:197], v[106:109]
	v_mfma_f32_16x16x32_bf16 v[94:97], v[146:149], v[202:205], v[94:97]
	v_mfma_f32_16x16x32_bf16 v[90:93], v[162:165], v[202:205], v[90:93]
	v_mfma_f32_16x16x32_bf16 v[78:81], v[146:149], v[210:213], v[78:81]
	v_mfma_f32_16x16x32_bf16 v[74:77], v[162:165], v[210:213], v[74:77]
	v_mfma_f32_16x16x32_bf16 v[126:129], v[158:161], v[190:193], v[126:129]
	v_mfma_f32_16x16x32_bf16 v[122:125], v[166:169], v[190:193], v[122:125]
	v_mfma_f32_16x16x32_bf16 v[110:113], v[158:161], v[198:201], v[110:113]
	v_mfma_f32_16x16x32_bf16 v[106:109], v[166:169], v[198:201], v[106:109]
	v_mfma_f32_16x16x32_bf16 v[94:97], v[158:161], v[206:209], v[94:97]
	v_mfma_f32_16x16x32_bf16 v[90:93], v[166:169], v[206:209], v[90:93]
	v_mfma_f32_16x16x32_bf16 v[78:81], v[158:161], v[214:217], v[78:81]
	v_mfma_f32_16x16x32_bf16 v[74:77], v[166:169], v[214:217], v[74:77]
	v_mfma_f32_16x16x32_bf16 v[118:121], v[170:173], v[186:189], v[118:121]
	v_mfma_f32_16x16x32_bf16 v[114:117], v[178:181], v[186:189], v[114:117]
	v_mfma_f32_16x16x32_bf16 v[102:105], v[170:173], v[194:197], v[102:105]
	v_mfma_f32_16x16x32_bf16 v[98:101], v[178:181], v[194:197], v[98:101]
	v_mfma_f32_16x16x32_bf16 v[86:89], v[170:173], v[202:205], v[86:89]
	v_mfma_f32_16x16x32_bf16 v[82:85], v[178:181], v[202:205], v[82:85]
	v_mfma_f32_16x16x32_bf16 v[70:73], v[170:173], v[210:213], v[70:73]
	v_mfma_f32_16x16x32_bf16 v[66:69], v[178:181], v[210:213], v[66:69]
	v_mfma_f32_16x16x32_bf16 v[118:121], v[174:177], v[190:193], v[118:121]
	v_mfma_f32_16x16x32_bf16 v[114:117], v[182:185], v[190:193], v[114:117]
	v_mfma_f32_16x16x32_bf16 v[102:105], v[174:177], v[198:201], v[102:105]
	v_mfma_f32_16x16x32_bf16 v[98:101], v[182:185], v[198:201], v[98:101]
	v_mfma_f32_16x16x32_bf16 v[86:89], v[174:177], v[206:209], v[86:89]
	v_mfma_f32_16x16x32_bf16 v[82:85], v[182:185], v[206:209], v[82:85]
	v_mfma_f32_16x16x32_bf16 v[70:73], v[174:177], v[214:217], v[70:73]
	v_mfma_f32_16x16x32_bf16 v[66:69], v[182:185], v[214:217], v[66:69]
	s_barrier
; #define PG8_STAGE(bufoff, gbase, voff) do { _Pragma("unroll") for (int _i = 0; _i < 2; ++_i) \
;         __builtin_amdgcn_global_load_lds((const unsigned*)((const char*)(gbase) + (voff)[_i]), (PG8_LAS unsigned*)(lds + (bufoff) + ldsw + _i * 8192), 16, 0, 0); } while (0)
; #define PG8_LDA(dst, b, h) do { _Pragma("unroll") for (int m = 0; m < 4; ++m) _Pragma("unroll") for (int k = 0; k < 2; ++k) dst[m][k] = *(const PG8_LAS bf16x8*)(lds + PG8_SA(b, h) + aoff + m * 2048 + k * 1024); } while (0)
; #define PG8_LDB(dst, b, h) do { _Pragma("unroll") for (int n = 0; n < 2; ++n) _Pragma("unroll") for (int k = 0; k < 2; ++k) dst[n][k] = *(const PG8_LAS bf16x8*)(lds + PG8_SB(b, h) + boff + n * 2048 + k * 1024); } while (0)
; #define PG8_MMA(ai, bj, At, Bt) do { __builtin_amdgcn_s_setprio(1); _Pragma("unroll") for (int m = 0; m < 4; ++m) _Pragma("unroll") for (int n = 0; n < 2; ++n) _Pragma("unroll") for (int k = 0; k < 2; ++k) \
;         acc[ai][bj][m][n] = __builtin_amdgcn_mfma_f32_16x16x32_bf16(Bt[n][k], At[m][k], acc[ai][bj][m][n], 0, 0, 0); __builtin_amdgcn_s_setprio(0); } while (0)
; #define PG8_WAIT_V(n) asm volatile("s_waitcnt vmcnt(" #n ")" ::: "memory")
; #define PG8_WAIT_L(n) asm volatile("s_waitcnt lgkmcnt(" #n ")" ::: "memory")
; #define PG8_BAR __builtin_amdgcn_s_barrier()
; #define PG8_SCHED __builtin_amdgcn_sched_barrier(0)
; template <class Epi, class Sched, bool ALIGN_EPI = false, bool SP2 = false>
; __device__ __forceinline__ void gemm_phase(PG8_LAS unsigned char* lds, const Gemm g, const Sched& S, const Epi& E) {
;     ...
;             PG8_LDB(B0, 0, 0); PG8_LDB(B1, 0, 1); PG8_SCHED; PG8_LDA(At, 0, 0); PG8_STAGE(PG8_SA(1, 1), a1 + hstep, voffA);
;             PG8_WAIT_V(8); PG8_WAIT_L(0); PG8_BAR; PG8_MMA(0, 0, At, B0); PG8_MMA(0, 1, At, B1); PG8_BAR; PG8_SCHED;
;     ...
;             PG8_LDA(At, 1, 1); PG8_STAGE(PG8_SB(1, 0), b3, voffB); PG8_STAGE(PG8_SB(1, 1), b3 + hstepB, voffB); PG8_STAGE(PG8_SA(1, 0), a3, voffA);
;             PG8_WAIT_V(8); PG8_WAIT_L(0); PG8_BAR; PG8_MMA(1, 0, At, B0); PG8_MMA(1, 1, At, B1); PG8_BAR; PG8_SCHED;
	s_add_i32 s42, s62, s30
	v_lshl_add_u64 v[150:151], v[150:151], 0, s[10:11]
	s_mov_b32 m0, s42
	ds_read_b128 v[186:189], v156 offset:49152
	ds_read_b128 v[190:193], v156 offset:50176
	ds_read_b128 v[194:197], v156 offset:51200
	ds_read_b128 v[198:201], v156 offset:52224
	ds_read_b128 v[202:205], v156 offset:53248
	ds_read_b128 v[206:209], v156 offset:54272
	ds_read_b128 v[210:213], v156 offset:55296
	ds_read_b128 v[214:217], v156 offset:56320
	global_load_lds_dwordx4 v[150:151], off
	s_add_i32 m0, s42, 0x2000
	s_add_u32 s40, s40, 0x10080
	v_lshl_add_u64 v[150:151], v[218:219], 0, s[10:11]
	s_addc_u32 s41, s41, 0
	s_add_i32 s42, s63, s30
	global_load_lds_dwordx4 v[150:151], off
	s_mov_b32 m0, s42
	s_nop 0
	global_load_lds_dwordx4 v132, s[40:41]
	s_add_i32 m0, s42, 0x2000
	s_nop 0
	global_load_lds_dwordx4 v136, s[40:41]
	v_lshl_add_u64 v[150:151], v[220:221], 0, s[10:11]
	s_mov_b32 m0, s47
	s_nop 0
	global_load_lds_dwordx4 v[150:151], off
	v_lshl_add_u64 v[150:151], v[222:223], 0, s[10:11]
	s_mov_b32 m0, s54
	s_nop 0
	global_load_lds_dwordx4 v[150:151], off
	s_waitcnt vmcnt(8)
	s_waitcnt lgkmcnt(0)
	s_barrier
	v_mfma_f32_16x16x32_bf16 v[62:65], v[146:149], v[186:189], v[62:65]
	v_mfma_f32_16x16x32_bf16 v[58:61], v[162:165], v[186:189], v[58:61]
	v_mfma_f32_16x16x32_bf16 v[46:49], v[146:149], v[194:197], v[46:49]
	v_mfma_f32_16x16x32_bf16 v[42:45], v[162:165], v[194:197], v[42:45]
	v_mfma_f32_16x16x32_bf16 v[30:33], v[146:149], v[202:205], v[30:33]
	v_mfma_f32_16x16x32_bf16 v[26:29], v[162:165], v[202:205], v[26:29]
	v_mfma_f32_16x16x32_bf16 v[14:17], v[146:149], v[210:213], v[14:17]
	v_mfma_f32_16x16x32_bf16 v[10:13], v[162:165], v[210:213], v[10:13]
	v_mfma_f32_16x16x32_bf16 v[62:65], v[158:161], v[190:193], v[62:65]
	v_mfma_f32_16x16x32_bf16 v[58:61], v[166:169], v[190:193], v[58:61]
	v_mfma_f32_16x16x32_bf16 v[46:49], v[158:161], v[198:201], v[46:49]
	v_mfma_f32_16x16x32_bf16 v[42:45], v[166:169], v[198:201], v[42:45]
	v_mfma_f32_16x16x32_bf16 v[30:33], v[158:161], v[206:209], v[30:33]
	v_mfma_f32_16x16x32_bf16 v[26:29], v[166:169], v[206:209], v[26:29]
	v_mfma_f32_16x16x32_bf16 v[14:17], v[158:161], v[214:217], v[14:17]
	v_mfma_f32_16x16x32_bf16 v[10:13], v[166:169], v[214:217], v[10:13]
	v_mfma_f32_16x16x32_bf16 v[54:57], v[170:173], v[186:189], v[54:57]
	v_mfma_f32_16x16x32_bf16 v[50:53], v[178:181], v[186:189], v[50:53]
	v_mfma_f32_16x16x32_bf16 v[38:41], v[170:173], v[194:197], v[38:41]
	v_mfma_f32_16x16x32_bf16 v[34:37], v[178:181], v[194:197], v[34:37]
	v_mfma_f32_16x16x32_bf16 v[22:25], v[170:173], v[202:205], v[22:25]
	v_mfma_f32_16x16x32_bf16 v[18:21], v[178:181], v[202:205], v[18:21]
	v_mfma_f32_16x16x32_bf16 v[6:9], v[170:173], v[210:213], v[6:9]
	v_mfma_f32_16x16x32_bf16 v[2:5], v[178:181], v[210:213], v[2:5]
	v_mfma_f32_16x16x32_bf16 v[54:57], v[174:177], v[190:193], v[54:57]
	v_mfma_f32_16x16x32_bf16 v[50:53], v[182:185], v[190:193], v[50:53]
	v_mfma_f32_16x16x32_bf16 v[38:41], v[174:177], v[198:201], v[38:41]
	v_mfma_f32_16x16x32_bf16 v[34:37], v[182:185], v[198:201], v[34:37]
	v_mfma_f32_16x16x32_bf16 v[22:25], v[174:177], v[206:209], v[22:25]
	v_mfma_f32_16x16x32_bf16 v[18:21], v[182:185], v[206:209], v[18:21]
	v_mfma_f32_16x16x32_bf16 v[6:9], v[174:177], v[214:217], v[6:9]
	v_mfma_f32_16x16x32_bf16 v[2:5], v[182:185], v[214:217], v[2:5]
	s_barrier
	s_add_i32 s61, s61, 2
	s_add_u32 s38, s38, 0x100
	s_addc_u32 s39, s39, 0
	s_add_u32 s59, s59, 0x100
	s_addc_u32 s60, s60, 0
	s_cmp_gt_u32 s61, 13
	s_cbranch_scc1 .Lpp1_x
.LBB0_1313:
	ds_read_b128 v[146:149], v154
	ds_read_b128 v[158:161], v154 offset:1024
	ds_read_b128 v[162:165], v154 offset:2048
	ds_read_b128 v[166:169], v154 offset:3072
	ds_read_b128 v[170:173], v155
	ds_read_b128 v[174:177], v155 offset:1024
	ds_read_b128 v[178:181], v155 offset:2048
	ds_read_b128 v[182:185], v155 offset:3072
	s_add_u32 s40, s38, 0xfffc0080
	s_addc_u32 s41, s39, -1
	s_cmp_eq_u32 s61, 12
	s_cselect_b32 s43, s9, s41
	s_cselect_b32 s42, s27, s40
	s_cselect_b32 s41, s25, s60
	s_cselect_b32 s40, s37, s59
	s_add_i32 m0, s31, 0xc000
	ds_read_b128 v[186:189], v156
	ds_read_b128 v[190:193], v156 offset:1024
	ds_read_b128 v[194:197], v156 offset:2048
	ds_read_b128 v[198:201], v156 offset:3072
	ds_read_b128 v[202:205], v156 offset:4096
	ds_read_b128 v[206:209], v156 offset:5120
	ds_read_b128 v[210:213], v156 offset:6144
	ds_read_b128 v[214:217], v156 offset:7168
	global_load_lds_dwordx4 v138, s[38:39]
	s_add_i32 m0, s31, 0xe000
	s_nop 0
	global_load_lds_dwordx4 v140, s[38:39]
	s_waitcnt vmcnt(8)
	s_waitcnt lgkmcnt(0)
	s_barrier
; #define PG8_STAGE(bufoff, gbase, voff) do { _Pragma("unroll") for (int _i = 0; _i < 2; ++_i) \
;         __builtin_amdgcn_global_load_lds((const unsigned*)((const char*)(gbase) + (voff)[_i]), (PG8_LAS unsigned*)(lds + (bufoff) + ldsw + _i * 8192), 16, 0, 0); } while (0)
; #define PG8_LDA(dst, b, h) do { _Pragma("unroll") for (int m = 0; m < 4; ++m) _Pragma("unroll") for (int k = 0; k < 2; ++k) dst[m][k] = *(const PG8_LAS bf16x8*)(lds + PG8_SA(b, h) + aoff + m * 2048 + k * 1024); } while (0)
; #define PG8_MMA(ai, bj, At, Bt) do { __builtin_amdgcn_s_setprio(1); _Pragma("unroll") for (int m = 0; m < 4; ++m) _Pragma("unroll") for (int n = 0; n < 2; ++n) _Pragma("unroll") for (int k = 0; k < 2; ++k) \
;         acc[ai][bj][m][n] = __builtin_amdgcn_mfma_f32_16x16x32_bf16(Bt[n][k], At[m][k], acc[ai][bj][m][n], 0, 0, 0); __builtin_amdgcn_s_setprio(0); } while (0)
; #define PG8_WAIT_V(n) asm volatile("s_waitcnt vmcnt(" #n ")" ::: "memory")
; #define PG8_WAIT_L(n) asm volatile("s_waitcnt lgkmcnt(" #n ")" ::: "memory")
; #define PG8_BAR __builtin_amdgcn_s_barrier()
; #define PG8_SCHED __builtin_amdgcn_sched_barrier(0)
; template <class Epi, class Sched, bool ALIGN_EPI = false, bool SP2 = false>
; __device__ __forceinline__ void gemm_phase(PG8_LAS unsigned char* lds, const Gemm g, const Sched& S, const Epi& E) {
;     ...
;             PG8_WAIT_V(8); PG8_WAIT_L(0); PG8_BAR; PG8_MMA(0, 0, At, B0); PG8_MMA(0, 1, At, B1); PG8_BAR; PG8_SCHED;
;             PG8_LDA(At, 0, 1); PG8_STAGE(PG8_SB(0, 0), b2, voffB); PG8_STAGE(PG8_SB(0, 1), b2 + hstepB, voffB); PG8_STAGE(PG8_SA(0, 0), a2, voffA);
;             PG8_WAIT_V(8); PG8_WAIT_L(0); PG8_BAR; PG8_MMA(1, 0, At, B0); PG8_MMA(1, 1, At, B1); PG8_BAR; PG8_SCHED;
	v_mfma_f32_16x16x32_bf16 v[126:129], v[146:149], v[186:189], v[126:129]
	v_mfma_f32_16x16x32_bf16 v[122:125], v[162:165], v[186:189], v[122:125]
	v_mfma_f32_16x16x32_bf16 v[110:113], v[146:149], v[194:197], v[110:113]
	v_mfma_f32_16x16x32_bf16 v[106:109], v[162:165], v[194:197], v[106:109]
	v_mfma_f32_16x16x32_bf16 v[94:97], v[146:149], v[202:205], v[94:97]
	v_mfma_f32_16x16x32_bf16 v[90:93], v[162:165], v[202:205], v[90:93]
	v_mfma_f32_16x16x32_bf16 v[78:81], v[146:149], v[210:213], v[78:81]
	v_mfma_f32_16x16x32_bf16 v[74:77], v[162:165], v[210:213], v[74:77]
	v_mfma_f32_16x16x32_bf16 v[126:129], v[158:161], v[190:193], v[126:129]
	v_mfma_f32_16x16x32_bf16 v[122:125], v[166:169], v[190:193], v[122:125]
	v_mfma_f32_16x16x32_bf16 v[110:113], v[158:161], v[198:201], v[110:113]
	v_mfma_f32_16x16x32_bf16 v[106:109], v[166:169], v[198:201], v[106:109]
	v_mfma_f32_16x16x32_bf16 v[94:97], v[158:161], v[206:209], v[94:97]
	v_mfma_f32_16x16x32_bf16 v[90:93], v[166:169], v[206:209], v[90:93]
	v_mfma_f32_16x16x32_bf16 v[78:81], v[158:161], v[214:217], v[78:81]
	v_mfma_f32_16x16x32_bf16 v[74:77], v[166:169], v[214:217], v[74:77]
	v_mfma_f32_16x16x32_bf16 v[118:121], v[170:173], v[186:189], v[118:121]
	v_mfma_f32_16x16x32_bf16 v[114:117], v[178:181], v[186:189], v[114:117]
	v_mfma_f32_16x16x32_bf16 v[102:105], v[170:173], v[194:197], v[102:105]
	v_mfma_f32_16x16x32_bf16 v[98:101], v[178:181], v[194:197], v[98:101]
	v_mfma_f32_16x16x32_bf16 v[86:89], v[170:173], v[202:205], v[86:89]
	v_mfma_f32_16x16x32_bf16 v[82:85], v[178:181], v[202:205], v[82:85]
	v_mfma_f32_16x16x32_bf16 v[70:73], v[170:173], v[210:213], v[70:73]
	v_mfma_f32_16x16x32_bf16 v[66:69], v[178:181], v[210:213], v[66:69]
	v_mfma_f32_16x16x32_bf16 v[118:121], v[174:177], v[190:193], v[118:121]
	v_mfma_f32_16x16x32_bf16 v[114:117], v[182:185], v[190:193], v[114:117]
	v_mfma_f32_16x16x32_bf16 v[102:105], v[174:177], v[198:201], v[102:105]
	v_mfma_f32_16x16x32_bf16 v[98:101], v[182:185], v[198:201], v[98:101]
	v_mfma_f32_16x16x32_bf16 v[86:89], v[174:177], v[206:209], v[86:89]
	v_mfma_f32_16x16x32_bf16 v[82:85], v[182:185], v[206:209], v[82:85]
	v_mfma_f32_16x16x32_bf16 v[70:73], v[174:177], v[214:217], v[70:73]
	v_mfma_f32_16x16x32_bf16 v[66:69], v[182:185], v[214:217], v[66:69]
	s_barrier
	s_add_i32 s62, s57, s30
	v_lshl_add_u64 v[150:151], s[40:41], 0, v[132:133]
	s_mov_b32 m0, s62
	ds_read_b128 v[186:189], v156 offset:16384
	ds_read_b128 v[190:193], v156 offset:17408
	ds_read_b128 v[194:197], v156 offset:18432
	ds_read_b128 v[198:201], v156 offset:19456
	ds_read_b128 v[202:205], v156 offset:20480
	ds_read_b128 v[206:209], v156 offset:21504
	ds_read_b128 v[210:213], v156 offset:22528
	ds_read_b128 v[214:217], v156 offset:23552
	global_load_lds_dwordx4 v132, s[40:41]
	s_add_i32 m0, s62, 0x2000
	s_add_u32 s62, s40, 0x10000
	v_lshl_add_u64 v[218:219], s[40:41], 0, v[136:137]
	s_addc_u32 s63, s41, 0
	s_add_i32 s64, s58, s30
	global_load_lds_dwordx4 v136, s[40:41]
	s_mov_b32 m0, s64
	v_lshl_add_u64 v[222:223], s[42:43], 0, v[134:135]
	global_load_lds_dwordx4 v132, s[62:63]
	s_add_i32 m0, s64, 0x2000
	s_nop 0
	global_load_lds_dwordx4 v136, s[62:63]
	v_lshl_add_u64 v[220:221], s[42:43], 0, v[130:131]
	s_mov_b32 m0, s31
	s_nop 0
	global_load_lds_dwordx4 v130, s[42:43]
	s_mov_b32 m0, s33
	s_nop 0
	global_load_lds_dwordx4 v134, s[42:43]
	s_waitcnt vmcnt(8)
	s_waitcnt lgkmcnt(0)
	s_barrier
	v_mfma_f32_16x16x32_bf16 v[62:65], v[146:149], v[186:189], v[62:65]
	v_mfma_f32_16x16x32_bf16 v[58:61], v[162:165], v[186:189], v[58:61]
	v_mfma_f32_16x16x32_bf16 v[46:49], v[146:149], v[194:197], v[46:49]
	v_mfma_f32_16x16x32_bf16 v[42:45], v[162:165], v[194:197], v[42:45]
	v_mfma_f32_16x16x32_bf16 v[30:33], v[146:149], v[202:205], v[30:33]
	v_mfma_f32_16x16x32_bf16 v[26:29], v[162:165], v[202:205], v[26:29]
	v_mfma_f32_16x16x32_bf16 v[14:17], v[146:149], v[210:213], v[14:17]
	v_mfma_f32_16x16x32_bf16 v[10:13], v[162:165], v[210:213], v[10:13]
	v_mfma_f32_16x16x32_bf16 v[62:65], v[158:161], v[190:193], v[62:65]
	v_mfma_f32_16x16x32_bf16 v[58:61], v[166:169], v[190:193], v[58:61]
	v_mfma_f32_16x16x32_bf16 v[46:49], v[158:161], v[198:201], v[46:49]
	v_mfma_f32_16x16x32_bf16 v[42:45], v[166:169], v[198:201], v[42:45]
	v_mfma_f32_16x16x32_bf16 v[30:33], v[158:161], v[206:209], v[30:33]
	v_mfma_f32_16x16x32_bf16 v[26:29], v[166:169], v[206:209], v[26:29]
	v_mfma_f32_16x16x32_bf16 v[14:17], v[158:161], v[214:217], v[14:17]
	v_mfma_f32_16x16x32_bf16 v[10:13], v[166:169], v[214:217], v[10:13]
	v_mfma_f32_16x16x32_bf16 v[54:57], v[170:173], v[186:189], v[54:57]
	v_mfma_f32_16x16x32_bf16 v[50:53], v[178:181], v[186:189], v[50:53]
	v_mfma_f32_16x16x32_bf16 v[38:41], v[170:173], v[194:197], v[38:41]
	v_mfma_f32_16x16x32_bf16 v[34:37], v[178:181], v[194:197], v[34:37]
	v_mfma_f32_16x16x32_bf16 v[22:25], v[170:173], v[202:205], v[22:25]
	v_mfma_f32_16x16x32_bf16 v[18:21], v[178:181], v[202:205], v[18:21]
	v_mfma_f32_16x16x32_bf16 v[6:9], v[170:173], v[210:213], v[6:9]
	v_mfma_f32_16x16x32_bf16 v[2:5], v[178:181], v[210:213], v[2:5]
	v_mfma_f32_16x16x32_bf16 v[54:57], v[174:177], v[190:193], v[54:57]
	v_mfma_f32_16x16x32_bf16 v[50:53], v[182:185], v[190:193], v[50:53]
	v_mfma_f32_16x16x32_bf16 v[38:41], v[174:177], v[198:201], v[38:41]
	v_mfma_f32_16x16x32_bf16 v[34:37], v[182:185], v[198:201], v[34:37]
	v_mfma_f32_16x16x32_bf16 v[22:25], v[174:177], v[206:209], v[22:25]
	v_mfma_f32_16x16x32_bf16 v[18:21], v[182:185], v[206:209], v[18:21]
	v_mfma_f32_16x16x32_bf16 v[6:9], v[174:177], v[214:217], v[6:9]
	v_mfma_f32_16x16x32_bf16 v[2:5], v[182:185], v[214:217], v[2:5]
	s_barrier
; #define PG8_STAGE(bufoff, gbase, voff) do { _Pragma("unroll") for (int _i = 0; _i < 2; ++_i) \
;         __builtin_amdgcn_global_load_lds((const unsigned*)((const char*)(gbase) + (voff)[_i]), (PG8_LAS unsigned*)(lds + (bufoff) + ldsw + _i * 8192), 16, 0, 0); } while (0)
; #define PG8_LDA(dst, b, h) do { _Pragma("unroll") for (int m = 0; m < 4; ++m) _Pragma("unroll") for (int k = 0; k < 2; ++k) dst[m][k] = *(const PG8_LAS bf16x8*)(lds + PG8_SA(b, h) + aoff + m * 2048 + k * 1024); } while (0)
; #define PG8_LDB(dst, b, h) do { _Pragma("unroll") for (int n = 0; n < 2; ++n) _Pragma("unroll") for (int k = 0; k < 2; ++k) dst[n][k] = *(const PG8_LAS bf16x8*)(lds + PG8_SB(b, h) + boff + n * 2048 + k * 1024); } while (0)
; #define PG8_MMA(ai, bj, At, Bt) do { __builtin_amdgcn_s_setprio(1); _Pragma("unroll") for (int m = 0; m < 4; ++m) _Pragma("unroll") for (int n = 0; n < 2; ++n) _Pragma("unroll") for (int k = 0; k < 2; ++k) \
;         acc[ai][bj][m][n] = __builtin_amdgcn_mfma_f32_16x16x32_bf16(Bt[n][k], At[m][k], acc[ai][bj][m][n], 0, 0, 0); __builtin_amdgcn_s_setprio(0); } while (0)
; #define PG8_WAIT_V(n) asm volatile("s_waitcnt vmcnt(" #n ")" ::: "memory")
; #define PG8_WAIT_L(n) asm volatile("s_waitcnt lgkmcnt(" #n ")" ::: "memory")
; #define PG8_BAR __builtin_amdgcn_s_barrier()
; #define PG8_SCHED __builtin_amdgcn_sched_barrier(0)
; template <class Epi, class Sched, bool ALIGN_EPI = false, bool SP2 = false>
; __device__ __forceinline__ void gemm_phase(PG8_LAS unsigned char* lds, const Gemm g, const Sched& S, const Epi& E) {
;     ...
;             PG8_LDB(B0, 1, 0); PG8_LDB(B1, 1, 1); PG8_SCHED; PG8_LDA(At, 1, 0); PG8_STAGE(PG8_SA(0, 1), a2 + hstep, voffA);
;             PG8_WAIT_V(8); PG8_WAIT_L(0); PG8_BAR; PG8_MMA(0, 0, At, B0); PG8_MMA(0, 1, At, B1); PG8_BAR; PG8_SCHED;
;             PG8_LDA(At, 1, 1); PG8_STAGE(PG8_SB(1, 0), b3, voffB); PG8_STAGE(PG8_SB(1, 1), b3 + hstepB, voffB); PG8_STAGE(PG8_SA(1, 0), a3, voffA);
;             PG8_WAIT_V(8); PG8_WAIT_L(0); PG8_BAR; PG8_MMA(1, 0, At, B0); PG8_MMA(1, 1, At, B1); PG8_BAR; PG8_SCHED;
	s_add_i32 s62, 0, 0x18000
	v_add_u32_e32 v157, s62, v152
	s_add_i32 s63, 0, 0x1c000
	ds_read_b128 v[146:149], v157
	ds_read_b128 v[158:161], v157 offset:1024
	ds_read_b128 v[162:165], v157 offset:2048
	ds_read_b128 v[166:169], v157 offset:3072
	v_add_u32_e32 v157, s63, v152
	ds_read_b128 v[170:173], v157
	ds_read_b128 v[174:177], v157 offset:1024
	ds_read_b128 v[178:181], v157 offset:2048
	ds_read_b128 v[182:185], v157 offset:3072
	s_add_u32 s42, s42, 0x40000
	s_addc_u32 s43, s43, 0
	s_mov_b32 m0, s44
	ds_read_b128 v[186:189], v156 offset:32768
	ds_read_b128 v[190:193], v156 offset:33792
	ds_read_b128 v[194:197], v156 offset:34816
	ds_read_b128 v[198:201], v156 offset:35840
	ds_read_b128 v[202:205], v156 offset:36864
	ds_read_b128 v[206:209], v156 offset:37888
	ds_read_b128 v[210:213], v156 offset:38912
	ds_read_b128 v[214:217], v156 offset:39936
	global_load_lds_dwordx4 v130, s[42:43]
	s_mov_b32 m0, s45
	s_nop 0
	global_load_lds_dwordx4 v134, s[42:43]
	s_waitcnt vmcnt(8)
	s_waitcnt lgkmcnt(0)
	s_barrier
	v_mfma_f32_16x16x32_bf16 v[126:129], v[146:149], v[186:189], v[126:129]
	v_mfma_f32_16x16x32_bf16 v[122:125], v[162:165], v[186:189], v[122:125]
	v_mfma_f32_16x16x32_bf16 v[110:113], v[146:149], v[194:197], v[110:113]
	v_mfma_f32_16x16x32_bf16 v[106:109], v[162:165], v[194:197], v[106:109]
	v_mfma_f32_16x16x32_bf16 v[94:97], v[146:149], v[202:205], v[94:97]
	v_mfma_f32_16x16x32_bf16 v[90:93], v[162:165], v[202:205], v[90:93]
	v_mfma_f32_16x16x32_bf16 v[78:81], v[146:149], v[210:213], v[78:81]
	v_mfma_f32_16x16x32_bf16 v[74:77], v[162:165], v[210:213], v[74:77]
	v_mfma_f32_16x16x32_bf16 v[126:129], v[158:161], v[190:193], v[126:129]
	v_mfma_f32_16x16x32_bf16 v[122:125], v[166:169], v[190:193], v[122:125]
	v_mfma_f32_16x16x32_bf16 v[110:113], v[158:161], v[198:201], v[110:113]
	v_mfma_f32_16x16x32_bf16 v[106:109], v[166:169], v[198:201], v[106:109]
	v_mfma_f32_16x16x32_bf16 v[94:97], v[158:161], v[206:209], v[94:97]
	v_mfma_f32_16x16x32_bf16 v[90:93], v[166:169], v[206:209], v[90:93]
	v_mfma_f32_16x16x32_bf16 v[78:81], v[158:161], v[214:217], v[78:81]
	v_mfma_f32_16x16x32_bf16 v[74:77], v[166:169], v[214:217], v[74:77]
	v_mfma_f32_16x16x32_bf16 v[118:121], v[170:173], v[186:189], v[118:121]
	v_mfma_f32_16x16x32_bf16 v[114:117], v[178:181], v[186:189], v[114:117]
	v_mfma_f32_16x16x32_bf16 v[102:105], v[170:173], v[194:197], v[102:105]
	v_mfma_f32_16x16x32_bf16 v[98:101], v[178:181], v[194:197], v[98:101]
	v_mfma_f32_16x16x32_bf16 v[86:89], v[170:173], v[202:205], v[86:89]
	v_mfma_f32_16x16x32_bf16 v[82:85], v[178:181], v[202:205], v[82:85]
	v_mfma_f32_16x16x32_bf16 v[70:73], v[170:173], v[210:213], v[70:73]
	v_mfma_f32_16x16x32_bf16 v[66:69], v[178:181], v[210:213], v[66:69]
	v_mfma_f32_16x16x32_bf16 v[118:121], v[174:177], v[190:193], v[118:121]
	v_mfma_f32_16x16x32_bf16 v[114:117], v[182:185], v[190:193], v[114:117]
	v_mfma_f32_16x16x32_bf16 v[102:105], v[174:177], v[198:201], v[102:105]
	v_mfma_f32_16x16x32_bf16 v[98:101], v[182:185], v[198:201], v[98:101]
	v_mfma_f32_16x16x32_bf16 v[86:89], v[174:177], v[206:209], v[86:89]
	v_mfma_f32_16x16x32_bf16 v[82:85], v[182:185], v[206:209], v[82:85]
	v_mfma_f32_16x16x32_bf16 v[70:73], v[174:177], v[214:217], v[70:73]
	v_mfma_f32_16x16x32_bf16 v[66:69], v[182:185], v[214:217], v[66:69]
	s_barrier
	s_add_i32 s42, s62, s30
	v_lshl_add_u64 v[150:151], v[150:151], 0, s[10:11]
	s_mov_b32 m0, s42
	ds_read_b128 v[186:189], v156 offset:49152
	ds_read_b128 v[190:193], v156 offset:50176
	ds_read_b128 v[194:197], v156 offset:51200
	ds_read_b128 v[198:201], v156 offset:52224
	ds_read_b128 v[202:205], v156 offset:53248
	ds_read_b128 v[206:209], v156 offset:54272
	ds_read_b128 v[210:213], v156 offset:55296
	ds_read_b128 v[214:217], v156 offset:56320
	global_load_lds_dwordx4 v[150:151], off
	s_add_i32 m0, s42, 0x2000
	s_add_u32 s40, s40, 0x10080
	v_lshl_add_u64 v[150:151], v[218:219], 0, s[10:11]
	s_addc_u32 s41, s41, 0
	s_add_i32 s42, s63, s30
	global_load_lds_dwordx4 v[150:151], off
	s_mov_b32 m0, s42
	s_nop 0
	global_load_lds_dwordx4 v132, s[40:41]
	s_add_i32 m0, s42, 0x2000
	s_nop 0
	global_load_lds_dwordx4 v136, s[40:41]
	v_lshl_add_u64 v[150:151], v[220:221], 0, s[10:11]
	s_mov_b32 m0, s47
	s_nop 0
	global_load_lds_dwordx4 v[150:151], off
	v_lshl_add_u64 v[150:151], v[222:223], 0, s[10:11]
	s_mov_b32 m0, s54
	s_nop 0
	global_load_lds_dwordx4 v[150:151], off
	s_waitcnt vmcnt(8)
	s_waitcnt lgkmcnt(0)
	s_barrier
	v_mfma_f32_16x16x32_bf16 v[62:65], v[146:149], v[186:189], v[62:65]
	v_mfma_f32_16x16x32_bf16 v[58:61], v[162:165], v[186:189], v[58:61]
	v_mfma_f32_16x16x32_bf16 v[46:49], v[146:149], v[194:197], v[46:49]
	v_mfma_f32_16x16x32_bf16 v[42:45], v[162:165], v[194:197], v[42:45]
	v_mfma_f32_16x16x32_bf16 v[30:33], v[146:149], v[202:205], v[30:33]
	v_mfma_f32_16x16x32_bf16 v[26:29], v[162:165], v[202:205], v[26:29]
	v_mfma_f32_16x16x32_bf16 v[14:17], v[146:149], v[210:213], v[14:17]
	v_mfma_f32_16x16x32_bf16 v[10:13], v[162:165], v[210:213], v[10:13]
	v_mfma_f32_16x16x32_bf16 v[62:65], v[158:161], v[190:193], v[62:65]
	v_mfma_f32_16x16x32_bf16 v[58:61], v[166:169], v[190:193], v[58:61]
	v_mfma_f32_16x16x32_bf16 v[46:49], v[158:161], v[198:201], v[46:49]
	v_mfma_f32_16x16x32_bf16 v[42:45], v[166:169], v[198:201], v[42:45]
	v_mfma_f32_16x16x32_bf16 v[30:33], v[158:161], v[206:209], v[30:33]
	v_mfma_f32_16x16x32_bf16 v[26:29], v[166:169], v[206:209], v[26:29]
	v_mfma_f32_16x16x32_bf16 v[14:17], v[158:161], v[214:217], v[14:17]
	v_mfma_f32_16x16x32_bf16 v[10:13], v[166:169], v[214:217], v[10:13]
	v_mfma_f32_16x16x32_bf16 v[54:57], v[170:173], v[186:189], v[54:57]
	v_mfma_f32_16x16x32_bf16 v[50:53], v[178:181], v[186:189], v[50:53]
	v_mfma_f32_16x16x32_bf16 v[38:41], v[170:173], v[194:197], v[38:41]
	v_mfma_f32_16x16x32_bf16 v[34:37], v[178:181], v[194:197], v[34:37]
	v_mfma_f32_16x16x32_bf16 v[22:25], v[170:173], v[202:205], v[22:25]
	v_mfma_f32_16x16x32_bf16 v[18:21], v[178:181], v[202:205], v[18:21]
	v_mfma_f32_16x16x32_bf16 v[6:9], v[170:173], v[210:213], v[6:9]
	v_mfma_f32_16x16x32_bf16 v[2:5], v[178:181], v[210:213], v[2:5]
	v_mfma_f32_16x16x32_bf16 v[54:57], v[174:177], v[190:193], v[54:57]
	v_mfma_f32_16x16x32_bf16 v[50:53], v[182:185], v[190:193], v[50:53]
	v_mfma_f32_16x16x32_bf16 v[38:41], v[174:177], v[198:201], v[38:41]
	v_mfma_f32_16x16x32_bf16 v[34:37], v[182:185], v[198:201], v[34:37]
	v_mfma_f32_16x16x32_bf16 v[22:25], v[174:177], v[206:209], v[22:25]
	v_mfma_f32_16x16x32_bf16 v[18:21], v[182:185], v[206:209], v[18:21]
	v_mfma_f32_16x16x32_bf16 v[6:9], v[174:177], v[214:217], v[6:9]
	v_mfma_f32_16x16x32_bf16 v[2:5], v[182:185], v[214:217], v[2:5]
	s_barrier
	s_add_i32 s61, s61, 2
	s_add_u32 s38, s38, 0x100
	s_addc_u32 s39, s39, 0
	s_add_u32 s59, s59, 0x100
	s_addc_u32 s60, s60, 0
	s_cmp_gt_u32 s61, 13
	s_cbranch_scc0 .LBB0_1313
